# row scales of the two PEER tables interleaved as 8-byte pairs: one gather per expert in the act sub-phase instead of two
# speedup vs baseline: 1.0090x; 1.0090x over previous
; __global__ void __launch_bounds__(NTHR, 2) k_main(Args a) {
;     ...
;         if (bid >= cfirst) for (int rr0 = ((bid - cfirst) * 8 + wave) * 4; rr0 < 2 * 16384; rr0 += (nb - cfirst) * 8 * 4) {
;             float4 v[4][4];
; #pragma unroll
;             for (int q = 0; q < 4; ++q) { const int rr = rr0 + q, which = rr >> 14, row = rr & 16383;
;                 typedef float f4v __attribute__((ext_vector_type(4))); const f4v* src4 = (const f4v*)((which ? a.peer_v : a.peer_u) + (size_t)row * D) + lane;
; #pragma unroll
;                 for (int jq = 0; jq < 4; ++jq) { const f4v t4 = __builtin_nontemporal_load(src4 + 64 * jq); v[q][jq] = make_float4(t4.x, t4.y, t4.z, t4.w); } }
; #pragma unroll
;             for (int q = 0; q < 4; ++q) { const int rr = rr0 + q, which = rr >> 14, row = rr & 16383;
;                 float ss = 0.f;
; #pragma unroll
;                 for (int jq = 0; jq < 4; ++jq) ss += v[q][jq].x * v[q][jq].x + v[q][jq].y * v[q][jq].y + v[q][jq].z * v[q][jq].z + v[q][jq].w * v[q][jq].w;
;                 ss = wave_sum(ss);
;                 const float step = ss > 0.f ? 0.335f * sqrtf(ss * (1.f / D)) : 1.f, inv = 1.f / step;
;                 unsigned short* dst = (unsigned short*)((which ? V8 : U8) + (size_t)row * 128) + lane;
; #pragma unroll
;                 for (int jq = 0; jq < 4; ++jq) { const float e4[4] = {v[q][jq].x, v[q][jq].y, v[q][jq].z, v[q][jq].w}; unsigned w4 = 0u;
; #pragma unroll
;                     for (int i = 0; i < 4; ++i) { const int qi = (int)fminf(fmaxf(floorf(e4[i] * inv), -8.f), 7.f); w4 |= ((unsigned)qi & 15u) << (4 * i); }
;                     dst[(size_t)jq * (16384 * 64)] = (unsigned short)w4; }
;                 if (lane == 0) (which ? SV : SU)[row] = 0.5f * step;
.LBB0_127:
	s_and_b32 s22, s11, 0x3ffc
	s_mov_b64 s[26:27], s[60:61]
	s_lshl_b32 s6, s22, 12
	v_readlane_b32 s60, v235, 16
	s_cmpk_lt_u32 s11, 0x4000
	v_readlane_b32 s74, v235, 30
	v_readlane_b32 s75, v235, 31
	s_cselect_b32 s1, s75, s85
	s_cselect_b32 s0, s74, s84
	v_lshl_add_u64 v[2:3], s[0:1], 0, v[64:65]
	v_lshl_add_u64 v[2:3], v[2:3], 0, s[6:7]
	global_load_dwordx4 v[72:75], v[2:3], off nt
	global_load_dwordx4 v[54:57], v[2:3], off offset:1024 nt
	global_load_dwordx4 v[50:53], v[2:3], off offset:2048 nt
	global_load_dwordx4 v[46:49], v[2:3], off offset:3072 nt
	v_readlane_b32 s8, v235, 36
	v_readlane_b32 s24, v235, 38
	v_add_co_u32_e32 v4, vcc, s13, v2
	s_cselect_b32 s1, s97, s51
	s_cselect_b32 s0, s96, s50
	s_cselect_b32 s24, 0, 4
	v_addc_co_u32_e32 v5, vcc, 0, v3, vcc
	v_lshl_add_u64 v[68:69], s[0:1], 0, v[66:67]
	v_add_co_u32_e32 v58, vcc, s14, v2
	global_load_dwordx4 v[42:45], v[4:5], off offset:1024 nt
	global_load_dwordx4 v[34:37], v[4:5], off offset:2048 nt
	v_addc_co_u32_e32 v59, vcc, 0, v3, vcc
	v_add_co_u32_e32 v2, vcc, s15, v2
	global_load_dwordx4 v[30:33], v[58:59], off nt
	global_load_dwordx4 v[26:29], v[58:59], off offset:1024 nt
	global_load_dwordx4 v[22:25], v[58:59], off offset:2048 nt
	global_load_dwordx4 v[18:21], v[58:59], off offset:3072 nt
	v_addc_co_u32_e32 v3, vcc, 0, v3, vcc
	v_readlane_b32 s9, v235, 37
	v_readlane_b32 s25, v235, 39
	s_or_b32 s8, s8, s24
	s_lshl_b32 s6, s22, 7
	v_lshl_add_u64 v[76:77], v[68:69], 0, s[6:7]
	v_readlane_b32 s61, v235, 17
	v_readlane_b32 s62, v235, 18
	v_readlane_b32 s63, v235, 19
	v_readlane_b32 s64, v235, 20
	v_readlane_b32 s65, v235, 21
	v_readlane_b32 s66, v235, 22
	v_readlane_b32 s67, v235, 23
	v_readlane_b32 s68, v235, 24
	v_readlane_b32 s69, v235, 25
	v_readlane_b32 s70, v235, 26
	v_readlane_b32 s71, v235, 27
	v_readlane_b32 s72, v235, 28
	v_readlane_b32 s73, v235, 29
	s_waitcnt vmcnt(9)
	v_mov_b32_e32 v8, v73
	s_waitcnt vmcnt(8)
	v_mov_b32_e32 v9, v55
	v_mov_b32_e32 v6, v72
	v_mov_b32_e32 v7, v54
	s_waitcnt vmcnt(7)
	v_mov_b32_e32 v16, v51
	s_waitcnt vmcnt(6)
	v_mov_b32_e32 v17, v47
	v_pk_mul_f32 v[8:9], v[8:9], v[8:9]
	v_mov_b32_e32 v10, v74
	v_mov_b32_e32 v11, v56
	v_mov_b32_e32 v14, v50
	v_mov_b32_e32 v15, v46
	v_pk_mul_f32 v[16:17], v[16:17], v[16:17]
	v_pk_fma_f32 v[6:7], v[6:7], v[6:7], v[8:9]
	v_mov_b32_e32 v12, v75
	v_mov_b32_e32 v13, v57
	v_mov_b32_e32 v38, v52
	v_mov_b32_e32 v39, v48
	v_pk_fma_f32 v[8:9], v[14:15], v[14:15], v[16:17]
	v_pk_fma_f32 v[6:7], v[10:11], v[10:11], v[6:7]
	v_mov_b32_e32 v40, v53
	v_mov_b32_e32 v41, v49
	v_pk_fma_f32 v[8:9], v[38:39], v[38:39], v[8:9]
	v_pk_fma_f32 v[6:7], v[12:13], v[12:13], v[6:7]
	v_pk_fma_f32 v[8:9], v[40:41], v[40:41], v[8:9]
	v_add_f32_e32 v6, v6, v7
	v_add_f32_e32 v6, v6, v8
	v_add_f32_e32 v6, v6, v9
	s_nop 1
	v_add_f32_dpp v6, v6, v6 quad_perm:[1,0,3,2] row_mask:0xf bank_mask:0xf bound_ctrl:1
	s_nop 1
	v_add_f32_dpp v6, v6, v6 quad_perm:[2,3,0,1] row_mask:0xf bank_mask:0xf bound_ctrl:1
	s_nop 1
	v_add_f32_dpp v6, v6, v6 row_half_mirror row_mask:0xf bank_mask:0xf bound_ctrl:1
	s_nop 1
	v_add_f32_dpp v6, v6, v6 row_mirror row_mask:0xf bank_mask:0xf bound_ctrl:1
	s_nop 0
	v_readlane_b32 s23, v6, 16
	v_readlane_b32 s24, v6, 48
	v_readlane_b32 s0, v6, 0
	v_readlane_b32 s1, v6, 32
	v_mov_b32_e32 v6, s23
	v_mov_b32_e32 v7, s24
	v_pk_add_f32 v[6:7], s[0:1], v[6:7]
	s_nop 0
	v_add_f32_e32 v60, v6, v7
	v_mul_f32_e32 v6, 0x3a800000, v60
	v_mul_f32_e32 v7, 0x4f800000, v6
	v_cmp_gt_f32_e32 vcc, s16, v6
	s_nop 1
	v_cndmask_b32_e32 v61, v6, v7, vcc
	v_sqrt_f32_e32 v71, v61
	global_load_dwordx4 v[38:41], v[4:5], off offset:3072 nt
	global_load_dwordx4 v[14:17], v[2:3], off nt
	global_load_dwordx4 v[10:13], v[2:3], off offset:1024 nt
	global_load_dwordx4 v[6:9], v[2:3], off offset:2048 nt
	v_add_u32_e32 v4, -1, v71
	v_add_u32_e32 v5, 1, v71
	v_fma_f32 v78, -v4, v71, v61
	v_fma_f32 v79, -v5, v71, v61
	v_cmp_ge_f32_e64 s[0:1], 0, v78
	s_nop 1
	v_cndmask_b32_e64 v4, v71, v4, s[0:1]
	v_cmp_lt_f32_e64 s[0:1], 0, v79
	s_nop 1
	v_cndmask_b32_e64 v4, v4, v5, s[0:1]
	v_mul_f32_e32 v5, 0x37800000, v4
	v_cndmask_b32_e32 v4, v4, v5, vcc
	v_cmp_class_f32_e32 vcc, v61, v63
	s_nop 1
	v_cndmask_b32_e32 v4, v4, v61, vcc
	v_mul_f32_e32 v4, 0x3eab851f, v4
	v_cmp_lt_f32_e32 vcc, 0, v60
	s_nop 1
	v_cndmask_b32_e32 v71, 1.0, v4, vcc
	global_load_dwordx4 v[58:61], v[58:59], off offset:-4096 nt
	s_nop 0
	global_load_dwordx4 v[2:5], v[2:3], off offset:3072 nt
	v_div_scale_f32 v78, s[0:1], v71, v71, 1.0
	v_rcp_f32_e32 v79, v78
	v_div_scale_f32 v80, vcc, 1.0, v71, 1.0
	v_fma_f32 v81, -v78, v79, 1.0
	v_fmac_f32_e32 v79, v81, v79
	v_mul_f32_e32 v81, v80, v79
	v_fma_f32 v82, -v78, v81, v80
	v_fmac_f32_e32 v81, v82, v79
	v_fma_f32 v78, -v78, v81, v80
	v_div_fmas_f32 v78, v78, v79, v81
	v_div_fixup_f32 v78, v78, v71, 1.0
	v_mul_f32_e32 v54, v78, v54
	v_mul_f32_e32 v55, v78, v55
	v_floor_f32_e32 v54, v54
	v_floor_f32_e32 v55, v55
	v_mul_f32_e32 v56, v78, v56
	v_med3_f32 v54, v54, s17, v70
	v_med3_f32 v55, v55, s17, v70
	v_floor_f32_e32 v56, v56
	v_cvt_i32_f32_e32 v54, v54
	v_cvt_i32_f32_e32 v55, v55
	v_med3_f32 v56, v56, s17, v70
	v_cvt_i32_f32_e32 v56, v56
	v_mul_f32_e32 v50, v78, v50
	v_and_b32_e32 v54, 15, v54
	v_lshlrev_b32_e32 v55, 4, v55
	v_floor_f32_e32 v50, v50
	v_mul_f32_e32 v57, v78, v57
	v_and_or_b32 v54, v55, s18, v54
	v_lshlrev_b32_e32 v55, 8, v56
	v_med3_f32 v50, v50, s17, v70
	v_floor_f32_e32 v57, v57
	v_and_or_b32 v54, v55, s19, v54
	v_cvt_i32_f32_e32 v55, v50
	v_mul_f32_e32 v50, v78, v51
	v_med3_f32 v57, v57, s17, v70
	v_floor_f32_e32 v50, v50
	v_mul_f32_e32 v52, v78, v52
	v_cvt_i32_f32_e32 v57, v57
	v_med3_f32 v50, v50, s17, v70
; __global__ void __launch_bounds__(NTHR, 2) k_main(Args a) {
;     ...
;             for (int q = 0; q < 4; ++q) { const int rr = rr0 + q, which = rr >> 14, row = rr & 16383;
;                 float ss = 0.f;
; #pragma unroll
;                 for (int jq = 0; jq < 4; ++jq) ss += v[q][jq].x * v[q][jq].x + v[q][jq].y * v[q][jq].y + v[q][jq].z * v[q][jq].z + v[q][jq].w * v[q][jq].w;
;                 ss = wave_sum(ss);
;                 const float step = ss > 0.f ? 0.335f * sqrtf(ss * (1.f / D)) : 1.f, inv = 1.f / step;
;                 unsigned short* dst = (unsigned short*)((which ? V8 : U8) + (size_t)row * 128) + lane;
; #pragma unroll
;                 for (int jq = 0; jq < 4; ++jq) { const float e4[4] = {v[q][jq].x, v[q][jq].y, v[q][jq].z, v[q][jq].w}; unsigned w4 = 0u;
; #pragma unroll
;                     for (int i = 0; i < 4; ++i) { const int qi = (int)fminf(fmaxf(floorf(e4[i] * inv), -8.f), 7.f); w4 |= ((unsigned)qi & 15u) << (4 * i); }
;                     dst[(size_t)jq * (16384 * 64)] = (unsigned short)w4; }
;                 if (lane == 0) (which ? SV : SU)[row] = 0.5f * step;
	v_floor_f32_e32 v52, v52
	v_cvt_i32_f32_e32 v56, v50
	v_med3_f32 v52, v52, s17, v70
	v_cvt_i32_f32_e32 v52, v52
	v_add_co_u32_e32 v50, vcc, s20, v76
	v_lshl_or_b32 v54, v57, 12, v54
	s_nop 0
	v_addc_co_u32_e32 v51, vcc, 0, v77, vcc
	v_mul_f32_e32 v46, v78, v46
	v_mov_b32_e32 v237, v54
	v_and_b32_e32 v50, 15, v55
	v_lshlrev_b32_e32 v51, 4, v56
	v_floor_f32_e32 v46, v46
	v_mul_f32_e32 v53, v78, v53
	v_and_or_b32 v50, v51, s18, v50
	v_lshlrev_b32_e32 v51, 8, v52
	v_med3_f32 v46, v46, s17, v70
	v_floor_f32_e32 v53, v53
	v_and_or_b32 v50, v51, s19, v50
	v_cvt_i32_f32_e32 v51, v46
	v_mul_f32_e32 v46, v78, v47
	v_mul_f32_e32 v72, v78, v72
	v_mul_f32_e32 v73, v78, v73
	v_med3_f32 v53, v53, s17, v70
	v_floor_f32_e32 v46, v46
	v_mul_f32_e32 v48, v78, v48
	v_mul_f32_e32 v74, v78, v74
	v_floor_f32_e32 v72, v72
	v_floor_f32_e32 v73, v73
	v_cvt_i32_f32_e32 v53, v53
	v_med3_f32 v46, v46, s17, v70
	v_floor_f32_e32 v48, v48
	v_floor_f32_e32 v74, v74
	v_med3_f32 v72, v72, s17, v70
	v_med3_f32 v73, v73, s17, v70
	v_cvt_i32_f32_e32 v52, v46
	v_med3_f32 v48, v48, s17, v70
	v_mul_f32_e32 v49, v78, v49
	v_mul_f32_e32 v75, v78, v75
	v_med3_f32 v74, v74, s17, v70
	v_cvt_i32_f32_e32 v72, v72
	v_cvt_i32_f32_e32 v73, v73
	v_cvt_i32_f32_e32 v48, v48
	v_floor_f32_e32 v49, v49
	v_floor_f32_e32 v75, v75
	v_cvt_i32_f32_e32 v74, v74
	v_add_co_u32_e32 v46, vcc, s21, v76
	v_med3_f32 v49, v49, s17, v70
	v_med3_f32 v75, v75, s17, v70
	v_lshl_or_b32 v50, v53, 12, v50
	v_addc_co_u32_e32 v47, vcc, 0, v77, vcc
	v_cvt_i32_f32_e32 v49, v49
	v_cvt_i32_f32_e32 v75, v75
	v_mov_b32_e32 v238, v50
	v_and_b32_e32 v46, 15, v51
	v_lshlrev_b32_e32 v47, 4, v52
	v_and_b32_e32 v72, 15, v72
	v_lshlrev_b32_e32 v73, 4, v73
	v_and_or_b32 v46, v47, s18, v46
	v_lshlrev_b32_e32 v47, 8, v48
	v_lshlrev_b32_e32 v74, 8, v74
	v_and_or_b32 v72, v73, s18, v72
	v_and_or_b32 v46, v47, s19, v46
	v_and_or_b32 v72, v74, s19, v72
	v_lshl_or_b32 v48, v49, 12, v46
	v_add_co_u32_e32 v46, vcc, 0x600000, v76
	v_lshl_or_b32 v72, v75, 12, v72
	s_nop 0
	v_addc_co_u32_e32 v47, vcc, 0, v77, vcc
	v_mov_b32_e32 v236, v72
	v_mov_b32_e32 v239, v48
	v_cndmask_b32_e64 v240, v237, v236, s[44:45]
	v_cndmask_b32_e64 v241, v239, v238, s[44:45]
	s_nop 1
	v_mov_b32_dpp v242, v240 quad_perm:[1,0,3,2] row_mask:0xf bank_mask:0xf
	v_mov_b32_dpp v243, v241 quad_perm:[1,0,3,2] row_mask:0xf bank_mask:0xf
	v_cndmask_b32_e64 v236, v236, v242, s[44:45]
	v_cndmask_b32_e64 v237, v242, v237, s[44:45]
	v_cndmask_b32_e64 v238, v238, v243, s[44:45]
	v_cndmask_b32_e64 v239, v243, v239, s[44:45]
	v_cndmask_b32_e64 v240, v238, v236, s[46:47]
	v_cndmask_b32_e64 v241, v239, v237, s[46:47]
	s_nop 1
	v_mov_b32_dpp v242, v240 quad_perm:[2,3,0,1] row_mask:0xf bank_mask:0xf
	v_mov_b32_dpp v243, v241 quad_perm:[2,3,0,1] row_mask:0xf bank_mask:0xf
	v_cndmask_b32_e64 v236, v236, v242, s[46:47]
	v_cndmask_b32_e64 v238, v242, v238, s[46:47]
	v_cndmask_b32_e64 v237, v237, v243, s[46:47]
	v_cndmask_b32_e64 v239, v243, v239, s[46:47]
	v_perm_b32 v248, v237, v236, s48
	v_perm_b32 v249, v239, v238, s48
	v_lshl_add_u64 v[246:247], v[76:77], 0, v[244:245]
	global_store_dwordx2 v[246:247], v[248:249], off
	s_and_saveexec_b64 s[0:1], s[4:5]
	s_cbranch_execz .LBB0_129
	s_lshl_b32 s23, s22, 3
	v_mul_f32_e32 v46, 0.5, v71
	v_mov_b32_e32 v47, s23
	global_store_dword v47, v46, s[8:9]
.LBB0_129:
	s_or_b64 exec, exec, s[0:1]
	s_waitcnt vmcnt(2)
	v_mov_b32_e32 v48, v59
	v_mov_b32_e32 v49, v43
	v_mov_b32_e32 v46, v58
	v_mov_b32_e32 v47, v42
	v_pk_mul_f32 v[48:49], v[48:49], v[48:49]
	v_mov_b32_e32 v50, v60
	v_mov_b32_e32 v51, v44
	v_pk_fma_f32 v[46:47], v[46:47], v[46:47], v[48:49]
	v_mov_b32_e32 v52, v61
	v_pk_fma_f32 v[46:47], v[50:51], v[50:51], v[46:47]
	v_mov_b32_e32 v50, v35
	v_mov_b32_e32 v51, v39
	v_mov_b32_e32 v53, v45
	v_mov_b32_e32 v48, v34
	v_mov_b32_e32 v49, v38
	v_pk_mul_f32 v[50:51], v[50:51], v[50:51]
	v_pk_fma_f32 v[46:47], v[52:53], v[52:53], v[46:47]
	v_mov_b32_e32 v52, v36
	v_mov_b32_e32 v53, v40
	v_pk_fma_f32 v[48:49], v[48:49], v[48:49], v[50:51]
	v_mov_b32_e32 v54, v37
	v_mov_b32_e32 v55, v41
	v_pk_fma_f32 v[48:49], v[52:53], v[52:53], v[48:49]
	v_add_f32_e32 v46, v46, v47
	v_pk_fma_f32 v[48:49], v[54:55], v[54:55], v[48:49]
	s_nop 0
	v_add_f32_e32 v46, v46, v48
	v_add_f32_e32 v46, v46, v49
	s_nop 1
	v_add_f32_dpp v46, v46, v46 quad_perm:[1,0,3,2] row_mask:0xf bank_mask:0xf bound_ctrl:1
	s_nop 1
	v_add_f32_dpp v46, v46, v46 quad_perm:[2,3,0,1] row_mask:0xf bank_mask:0xf bound_ctrl:1
	s_nop 1
	v_add_f32_dpp v46, v46, v46 row_half_mirror row_mask:0xf bank_mask:0xf bound_ctrl:1
	s_nop 1
	v_add_f32_dpp v46, v46, v46 row_mirror row_mask:0xf bank_mask:0xf bound_ctrl:1
	s_nop 0
	v_readlane_b32 s23, v46, 16
	v_readlane_b32 s24, v46, 48
	v_readlane_b32 s0, v46, 0
	v_readlane_b32 s1, v46, 32
	v_mov_b32_e32 v46, s23
	v_mov_b32_e32 v47, s24
	v_pk_add_f32 v[46:47], s[0:1], v[46:47]
	s_nop 0
	v_add_f32_e32 v46, v46, v47
	v_mul_f32_e32 v47, 0x3a800000, v46
	v_mul_f32_e32 v48, 0x4f800000, v47
	v_cmp_gt_f32_e32 vcc, s16, v47
	s_nop 1
	v_cndmask_b32_e32 v47, v47, v48, vcc
	v_sqrt_f32_e32 v48, v47
	s_nop 0
	v_add_u32_e32 v49, -1, v48
	v_fma_f32 v50, -v49, v48, v47
	v_cmp_ge_f32_e64 s[0:1], 0, v50
	v_add_u32_e32 v50, 1, v48
	s_nop 0
	v_cndmask_b32_e64 v49, v48, v49, s[0:1]
	v_fma_f32 v48, -v50, v48, v47
	v_cmp_lt_f32_e64 s[0:1], 0, v48
	s_nop 1
	v_cndmask_b32_e64 v48, v49, v50, s[0:1]
	v_mul_f32_e32 v49, 0x37800000, v48
	v_cndmask_b32_e32 v48, v48, v49, vcc
	v_cmp_class_f32_e32 vcc, v47, v63
	s_nop 1
	v_cndmask_b32_e32 v47, v48, v47, vcc
	v_mul_f32_e32 v47, 0x3eab851f, v47
	v_cmp_lt_f32_e32 vcc, 0, v46
	s_nop 1
	v_cndmask_b32_e32 v46, 1.0, v47, vcc
	v_div_scale_f32 v47, s[0:1], v46, v46, 1.0
; __global__ void __launch_bounds__(NTHR, 2) k_main(Args a) {
;     ...
;             for (int q = 0; q < 4; ++q) { const int rr = rr0 + q, which = rr >> 14, row = rr & 16383;
;                 float ss = 0.f;
; #pragma unroll
;                 for (int jq = 0; jq < 4; ++jq) ss += v[q][jq].x * v[q][jq].x + v[q][jq].y * v[q][jq].y + v[q][jq].z * v[q][jq].z + v[q][jq].w * v[q][jq].w;
;                 ss = wave_sum(ss);
;                 const float step = ss > 0.f ? 0.335f * sqrtf(ss * (1.f / D)) : 1.f, inv = 1.f / step;
;                 unsigned short* dst = (unsigned short*)((which ? V8 : U8) + (size_t)row * 128) + lane;
; #pragma unroll
;                 for (int jq = 0; jq < 4; ++jq) { const float e4[4] = {v[q][jq].x, v[q][jq].y, v[q][jq].z, v[q][jq].w}; unsigned w4 = 0u;
; #pragma unroll
;                     for (int i = 0; i < 4; ++i) { const int qi = (int)fminf(fmaxf(floorf(e4[i] * inv), -8.f), 7.f); w4 |= ((unsigned)qi & 15u) << (4 * i); }
;                     dst[(size_t)jq * (16384 * 64)] = (unsigned short)w4; }
;                 if (lane == 0) (which ? SV : SU)[row] = 0.5f * step;
	v_rcp_f32_e32 v48, v47
	s_or_b32 s0, s6, 0x80
	s_mov_b32 s1, s7
	v_fma_f32 v49, -v47, v48, 1.0
	v_fmac_f32_e32 v48, v49, v48
	v_div_scale_f32 v49, vcc, 1.0, v46, 1.0
	v_mul_f32_e32 v50, v49, v48
	v_fma_f32 v51, -v47, v50, v49
	v_fmac_f32_e32 v50, v51, v48
	v_fma_f32 v47, -v47, v50, v49
	v_div_fmas_f32 v47, v47, v48, v50
	v_div_fixup_f32 v47, v47, v46, 1.0
	v_mul_f32_e32 v42, v47, v42
	v_mul_f32_e32 v43, v47, v43
	v_floor_f32_e32 v42, v42
	v_floor_f32_e32 v43, v43
	v_mul_f32_e32 v44, v47, v44
	v_med3_f32 v42, v42, s17, v70
	v_med3_f32 v43, v43, s17, v70
	v_floor_f32_e32 v44, v44
	v_cvt_i32_f32_e32 v42, v42
	v_cvt_i32_f32_e32 v43, v43
	v_med3_f32 v44, v44, s17, v70
	v_cvt_i32_f32_e32 v44, v44
	v_mul_f32_e32 v34, v47, v34
	v_and_b32_e32 v42, 15, v42
	v_lshlrev_b32_e32 v43, 4, v43
	v_floor_f32_e32 v34, v34
	v_mul_f32_e32 v45, v47, v45
	v_and_or_b32 v42, v43, s18, v42
	v_lshlrev_b32_e32 v43, 8, v44
	v_med3_f32 v34, v34, s17, v70
	v_floor_f32_e32 v45, v45
	v_and_or_b32 v42, v43, s19, v42
	v_cvt_i32_f32_e32 v43, v34
	v_mul_f32_e32 v34, v47, v35
	v_med3_f32 v45, v45, s17, v70
	v_floor_f32_e32 v34, v34
	v_mul_f32_e32 v36, v47, v36
	v_cvt_i32_f32_e32 v45, v45
	v_med3_f32 v34, v34, s17, v70
	v_floor_f32_e32 v36, v36
	v_cvt_i32_f32_e32 v44, v34
	v_med3_f32 v36, v36, s17, v70
	v_mul_f32_e32 v37, v47, v37
	v_lshl_add_u64 v[48:49], v[68:69], 0, s[0:1]
	v_cvt_i32_f32_e32 v36, v36
	v_floor_f32_e32 v37, v37
	v_add_co_u32_e32 v34, vcc, s20, v48
	v_med3_f32 v37, v37, s17, v70
	v_lshl_or_b32 v42, v45, 12, v42
	v_addc_co_u32_e32 v35, vcc, 0, v49, vcc
	v_cvt_i32_f32_e32 v37, v37
	v_mov_b32_e32 v237, v42
	v_and_b32_e32 v34, 15, v43
	v_lshlrev_b32_e32 v35, 4, v44
	v_and_or_b32 v34, v35, s18, v34
	v_lshlrev_b32_e32 v35, 8, v36
	v_and_or_b32 v34, v35, s19, v34
	v_lshl_or_b32 v36, v37, 12, v34
	v_mul_f32_e32 v34, v47, v38
	v_floor_f32_e32 v34, v34
	v_mul_f32_e32 v50, v47, v58
	v_mul_f32_e32 v51, v47, v59
	v_med3_f32 v34, v34, s17, v70
	v_floor_f32_e32 v50, v50
	v_floor_f32_e32 v51, v51
	v_mul_f32_e32 v52, v47, v60
	v_cvt_i32_f32_e32 v37, v34
	v_mul_f32_e32 v34, v47, v39
	v_med3_f32 v50, v50, s17, v70
	v_med3_f32 v51, v51, s17, v70
	v_floor_f32_e32 v52, v52
	v_floor_f32_e32 v34, v34
	v_cvt_i32_f32_e32 v50, v50
	v_cvt_i32_f32_e32 v51, v51
	v_med3_f32 v52, v52, s17, v70
	v_med3_f32 v34, v34, s17, v70
	v_cvt_i32_f32_e32 v52, v52
	v_cvt_i32_f32_e32 v38, v34
	v_add_co_u32_e32 v34, vcc, s21, v48
	v_and_b32_e32 v50, 15, v50
	s_nop 0
	v_addc_co_u32_e32 v35, vcc, 0, v49, vcc
	v_mov_b32_e32 v238, v36
	v_mul_f32_e32 v36, v47, v40
	v_lshlrev_b32_e32 v51, 4, v51
	v_floor_f32_e32 v36, v36
	v_and_or_b32 v50, v51, s18, v50
	v_lshlrev_b32_e32 v51, 8, v52
	v_and_b32_e32 v34, 15, v37
	v_med3_f32 v36, v36, s17, v70
	v_mul_f32_e32 v37, v47, v41
	v_and_or_b32 v50, v51, s19, v50
	v_mul_f32_e32 v51, v47, v61
	v_cvt_i32_f32_e32 v36, v36
	v_floor_f32_e32 v37, v37
	v_floor_f32_e32 v51, v51
	v_med3_f32 v37, v37, s17, v70
	v_med3_f32 v51, v51, s17, v70
	v_cvt_i32_f32_e32 v37, v37
	v_cvt_i32_f32_e32 v51, v51
	v_lshlrev_b32_e32 v35, 4, v38
	v_and_or_b32 v34, v35, s18, v34
	v_lshlrev_b32_e32 v35, 8, v36
	v_and_or_b32 v34, v35, s19, v34
	v_lshl_or_b32 v36, v37, 12, v34
	v_add_co_u32_e32 v34, vcc, 0x600000, v48
	v_lshl_or_b32 v50, v51, 12, v50
	s_nop 0
	v_addc_co_u32_e32 v35, vcc, 0, v49, vcc
	v_mov_b32_e32 v236, v50
	v_mov_b32_e32 v239, v36
	v_cndmask_b32_e64 v240, v237, v236, s[44:45]
	v_cndmask_b32_e64 v241, v239, v238, s[44:45]
	s_nop 1
	v_mov_b32_dpp v242, v240 quad_perm:[1,0,3,2] row_mask:0xf bank_mask:0xf
	v_mov_b32_dpp v243, v241 quad_perm:[1,0,3,2] row_mask:0xf bank_mask:0xf
	v_cndmask_b32_e64 v236, v236, v242, s[44:45]
	v_cndmask_b32_e64 v237, v242, v237, s[44:45]
	v_cndmask_b32_e64 v238, v238, v243, s[44:45]
	v_cndmask_b32_e64 v239, v243, v239, s[44:45]
	v_cndmask_b32_e64 v240, v238, v236, s[46:47]
	v_cndmask_b32_e64 v241, v239, v237, s[46:47]
	s_nop 1
	v_mov_b32_dpp v242, v240 quad_perm:[2,3,0,1] row_mask:0xf bank_mask:0xf
	v_mov_b32_dpp v243, v241 quad_perm:[2,3,0,1] row_mask:0xf bank_mask:0xf
	v_cndmask_b32_e64 v236, v236, v242, s[46:47]
	v_cndmask_b32_e64 v238, v242, v238, s[46:47]
	v_cndmask_b32_e64 v237, v237, v243, s[46:47]
	v_cndmask_b32_e64 v239, v243, v239, s[46:47]
	v_perm_b32 v248, v237, v236, s48
	v_perm_b32 v249, v239, v238, s48
	v_lshl_add_u64 v[246:247], v[48:49], 0, v[244:245]
	global_store_dwordx2 v[246:247], v[248:249], off
	s_and_saveexec_b64 s[0:1], s[4:5]
	s_cbranch_execz .LBB0_131
	s_lshl_b32 s23, s22, 3
	v_mul_f32_e32 v34, 0.5, v46
	v_mov_b32_e32 v35, s23
	global_store_dword v35, v34, s[8:9] offset:8
; __global__ void __launch_bounds__(NTHR, 2) k_main(Args a) {
;     ...
;             for (int q = 0; q < 4; ++q) { const int rr = rr0 + q, which = rr >> 14, row = rr & 16383;
;                 float ss = 0.f;
; #pragma unroll
;                 for (int jq = 0; jq < 4; ++jq) ss += v[q][jq].x * v[q][jq].x + v[q][jq].y * v[q][jq].y + v[q][jq].z * v[q][jq].z + v[q][jq].w * v[q][jq].w;
;                 ss = wave_sum(ss);
;                 const float step = ss > 0.f ? 0.335f * sqrtf(ss * (1.f / D)) : 1.f, inv = 1.f / step;
;                 unsigned short* dst = (unsigned short*)((which ? V8 : U8) + (size_t)row * 128) + lane;
; #pragma unroll
;                 for (int jq = 0; jq < 4; ++jq) { const float e4[4] = {v[q][jq].x, v[q][jq].y, v[q][jq].z, v[q][jq].w}; unsigned w4 = 0u;
; #pragma unroll
;                     for (int i = 0; i < 4; ++i) { const int qi = (int)fminf(fmaxf(floorf(e4[i] * inv), -8.f), 7.f); w4 |= ((unsigned)qi & 15u) << (4 * i); }
;                     dst[(size_t)jq * (16384 * 64)] = (unsigned short)w4; }
;                 if (lane == 0) (which ? SV : SU)[row] = 0.5f * step;
.LBB0_131:
	s_or_b64 exec, exec, s[0:1]
	v_mov_b32_e32 v36, v31
	v_mov_b32_e32 v37, v27
	v_mov_b32_e32 v34, v30
	v_mov_b32_e32 v35, v26
	v_pk_mul_f32 v[36:37], v[36:37], v[36:37]
	v_mov_b32_e32 v38, v32
	v_mov_b32_e32 v39, v28
	v_pk_fma_f32 v[34:35], v[34:35], v[34:35], v[36:37]
	v_mov_b32_e32 v40, v33
	v_pk_fma_f32 v[34:35], v[38:39], v[38:39], v[34:35]
	v_mov_b32_e32 v38, v23
	v_mov_b32_e32 v39, v19
	v_mov_b32_e32 v41, v29
	v_mov_b32_e32 v36, v22
	v_mov_b32_e32 v37, v18
	v_pk_mul_f32 v[38:39], v[38:39], v[38:39]
	v_pk_fma_f32 v[34:35], v[40:41], v[40:41], v[34:35]
	v_mov_b32_e32 v40, v24
	v_mov_b32_e32 v41, v20
	v_pk_fma_f32 v[36:37], v[36:37], v[36:37], v[38:39]
	v_mov_b32_e32 v42, v25
	v_mov_b32_e32 v43, v21
	v_pk_fma_f32 v[36:37], v[40:41], v[40:41], v[36:37]
	v_add_f32_e32 v34, v34, v35
	v_pk_fma_f32 v[36:37], v[42:43], v[42:43], v[36:37]
	s_nop 0
	v_add_f32_e32 v34, v34, v36
	v_add_f32_e32 v34, v34, v37
	s_nop 1
	v_add_f32_dpp v34, v34, v34 quad_perm:[1,0,3,2] row_mask:0xf bank_mask:0xf bound_ctrl:1
	s_nop 1
	v_add_f32_dpp v34, v34, v34 quad_perm:[2,3,0,1] row_mask:0xf bank_mask:0xf bound_ctrl:1
	s_nop 1
	v_add_f32_dpp v34, v34, v34 row_half_mirror row_mask:0xf bank_mask:0xf bound_ctrl:1
	s_nop 1
	v_add_f32_dpp v34, v34, v34 row_mirror row_mask:0xf bank_mask:0xf bound_ctrl:1
	s_nop 0
	v_readlane_b32 s23, v34, 16
	v_readlane_b32 s24, v34, 48
	v_readlane_b32 s0, v34, 0
	v_readlane_b32 s1, v34, 32
	v_mov_b32_e32 v34, s23
	v_mov_b32_e32 v35, s24
	v_pk_add_f32 v[34:35], s[0:1], v[34:35]
	s_nop 0
	v_add_f32_e32 v34, v34, v35
	v_mul_f32_e32 v35, 0x3a800000, v34
	v_mul_f32_e32 v36, 0x4f800000, v35
	v_cmp_gt_f32_e32 vcc, s16, v35
	s_nop 1
	v_cndmask_b32_e32 v35, v35, v36, vcc
	v_sqrt_f32_e32 v36, v35
	s_nop 0
	v_add_u32_e32 v37, -1, v36
	v_fma_f32 v38, -v37, v36, v35
	v_cmp_ge_f32_e64 s[0:1], 0, v38
	v_add_u32_e32 v38, 1, v36
	s_nop 0
	v_cndmask_b32_e64 v37, v36, v37, s[0:1]
	v_fma_f32 v36, -v38, v36, v35
	v_cmp_lt_f32_e64 s[0:1], 0, v36
	s_nop 1
	v_cndmask_b32_e64 v36, v37, v38, s[0:1]
	v_mul_f32_e32 v37, 0x37800000, v36
	v_cndmask_b32_e32 v36, v36, v37, vcc
	v_cmp_class_f32_e32 vcc, v35, v63
	s_nop 1
	v_cndmask_b32_e32 v35, v36, v35, vcc
	v_mul_f32_e32 v35, 0x3eab851f, v35
	v_cmp_lt_f32_e32 vcc, 0, v34
	s_nop 1
	v_cndmask_b32_e32 v34, 1.0, v35, vcc
	v_div_scale_f32 v35, s[0:1], v34, v34, 1.0
	v_rcp_f32_e32 v36, v35
	s_or_b32 s0, s6, 0x100
	s_mov_b32 s1, s7
	v_fma_f32 v37, -v35, v36, 1.0
	v_fmac_f32_e32 v36, v37, v36
	v_div_scale_f32 v37, vcc, 1.0, v34, 1.0
	v_mul_f32_e32 v38, v37, v36
	v_fma_f32 v39, -v35, v38, v37
	v_fmac_f32_e32 v38, v39, v36
	v_fma_f32 v35, -v35, v38, v37
	v_div_fmas_f32 v35, v35, v36, v38
	v_div_fixup_f32 v35, v35, v34, 1.0
	v_mul_f32_e32 v26, v35, v26
	v_mul_f32_e32 v27, v35, v27
	v_floor_f32_e32 v26, v26
	v_floor_f32_e32 v27, v27
	v_mul_f32_e32 v28, v35, v28
	v_med3_f32 v26, v26, s17, v70
	v_med3_f32 v27, v27, s17, v70
	v_floor_f32_e32 v28, v28
	v_cvt_i32_f32_e32 v26, v26
	v_cvt_i32_f32_e32 v27, v27
	v_med3_f32 v28, v28, s17, v70
	v_cvt_i32_f32_e32 v28, v28
	v_mul_f32_e32 v22, v35, v22
	v_and_b32_e32 v26, 15, v26
	v_lshlrev_b32_e32 v27, 4, v27
	v_floor_f32_e32 v22, v22
	v_mul_f32_e32 v29, v35, v29
	v_and_or_b32 v26, v27, s18, v26
	v_lshlrev_b32_e32 v27, 8, v28
	v_med3_f32 v22, v22, s17, v70
	v_floor_f32_e32 v29, v29
	v_and_or_b32 v26, v27, s19, v26
	v_cvt_i32_f32_e32 v27, v22
	v_mul_f32_e32 v22, v35, v23
	v_med3_f32 v29, v29, s17, v70
	v_floor_f32_e32 v22, v22
	v_mul_f32_e32 v24, v35, v24
	v_cvt_i32_f32_e32 v29, v29
	v_med3_f32 v22, v22, s17, v70
	v_floor_f32_e32 v24, v24
	v_cvt_i32_f32_e32 v28, v22
	v_med3_f32 v24, v24, s17, v70
	v_lshl_add_u64 v[36:37], v[68:69], 0, s[0:1]
	v_mul_f32_e32 v30, v35, v30
	v_mul_f32_e32 v31, v35, v31
	v_cvt_i32_f32_e32 v24, v24
	v_floor_f32_e32 v30, v30
	v_floor_f32_e32 v31, v31
	v_mul_f32_e32 v32, v35, v32
	v_add_co_u32_e32 v22, vcc, s20, v36
	v_med3_f32 v30, v30, s17, v70
	v_med3_f32 v31, v31, s17, v70
	v_floor_f32_e32 v32, v32
	v_lshl_or_b32 v26, v29, 12, v26
	v_addc_co_u32_e32 v23, vcc, 0, v37, vcc
	v_mul_f32_e32 v18, v35, v18
	v_cvt_i32_f32_e32 v30, v30
	v_cvt_i32_f32_e32 v31, v31
	v_med3_f32 v32, v32, s17, v70
	v_mov_b32_e32 v237, v26
	v_and_b32_e32 v22, 15, v27
	v_lshlrev_b32_e32 v23, 4, v28
	v_floor_f32_e32 v18, v18
	v_cvt_i32_f32_e32 v32, v32
	v_mul_f32_e32 v25, v35, v25
	v_and_or_b32 v22, v23, s18, v22
	v_lshlrev_b32_e32 v23, 8, v24
	v_med3_f32 v18, v18, s17, v70
	v_floor_f32_e32 v25, v25
	v_and_or_b32 v22, v23, s19, v22
	v_cvt_i32_f32_e32 v23, v18
	v_mul_f32_e32 v18, v35, v19
	v_med3_f32 v25, v25, s17, v70
	v_floor_f32_e32 v18, v18
	v_mul_f32_e32 v20, v35, v20
	v_and_b32_e32 v30, 15, v30
	v_lshlrev_b32_e32 v31, 4, v31
	v_cvt_i32_f32_e32 v25, v25
	v_med3_f32 v18, v18, s17, v70
	v_floor_f32_e32 v20, v20
	v_and_or_b32 v30, v31, s18, v30
	v_lshlrev_b32_e32 v31, 8, v32
	v_cvt_i32_f32_e32 v24, v18
	v_med3_f32 v20, v20, s17, v70
	v_mul_f32_e32 v21, v35, v21
	v_and_or_b32 v30, v31, s19, v30
	v_mul_f32_e32 v31, v35, v33
	v_cvt_i32_f32_e32 v20, v20
	v_floor_f32_e32 v21, v21
	v_floor_f32_e32 v31, v31
	v_add_co_u32_e32 v18, vcc, s21, v36
	v_med3_f32 v21, v21, s17, v70
	v_med3_f32 v31, v31, s17, v70
	v_lshl_or_b32 v22, v25, 12, v22
	v_addc_co_u32_e32 v19, vcc, 0, v37, vcc
	v_cvt_i32_f32_e32 v21, v21
	v_cvt_i32_f32_e32 v31, v31
	v_mov_b32_e32 v238, v22
	v_and_b32_e32 v18, 15, v23
	v_lshlrev_b32_e32 v19, 4, v24
	v_and_or_b32 v18, v19, s18, v18
	v_lshlrev_b32_e32 v19, 8, v20
	v_and_or_b32 v18, v19, s19, v18
	v_lshl_or_b32 v20, v21, 12, v18
	v_add_co_u32_e32 v18, vcc, 0x600000, v36
	v_lshl_or_b32 v30, v31, 12, v30
	s_nop 0
	v_addc_co_u32_e32 v19, vcc, 0, v37, vcc
	v_mov_b32_e32 v236, v30
	v_mov_b32_e32 v239, v20
	v_cndmask_b32_e64 v240, v237, v236, s[44:45]
	v_cndmask_b32_e64 v241, v239, v238, s[44:45]
	s_nop 1
	v_mov_b32_dpp v242, v240 quad_perm:[1,0,3,2] row_mask:0xf bank_mask:0xf
	v_mov_b32_dpp v243, v241 quad_perm:[1,0,3,2] row_mask:0xf bank_mask:0xf
	v_cndmask_b32_e64 v236, v236, v242, s[44:45]
	v_cndmask_b32_e64 v237, v242, v237, s[44:45]
	v_cndmask_b32_e64 v238, v238, v243, s[44:45]
	v_cndmask_b32_e64 v239, v243, v239, s[44:45]
	v_cndmask_b32_e64 v240, v238, v236, s[46:47]
	v_cndmask_b32_e64 v241, v239, v237, s[46:47]
	s_nop 1
	v_mov_b32_dpp v242, v240 quad_perm:[2,3,0,1] row_mask:0xf bank_mask:0xf
	v_mov_b32_dpp v243, v241 quad_perm:[2,3,0,1] row_mask:0xf bank_mask:0xf
	v_cndmask_b32_e64 v236, v236, v242, s[46:47]
	v_cndmask_b32_e64 v238, v242, v238, s[46:47]
	v_cndmask_b32_e64 v237, v237, v243, s[46:47]
	v_cndmask_b32_e64 v239, v243, v239, s[46:47]
	v_perm_b32 v248, v237, v236, s48
	v_perm_b32 v249, v239, v238, s48
	v_lshl_add_u64 v[246:247], v[36:37], 0, v[244:245]
	global_store_dwordx2 v[246:247], v[248:249], off
	s_and_saveexec_b64 s[0:1], s[4:5]
	s_mov_b64 s[60:61], s[26:27]
	s_cbranch_execz .LBB0_133
	s_lshl_b32 s23, s22, 3
	v_mul_f32_e32 v18, 0.5, v34
	v_mov_b32_e32 v19, s23
	global_store_dword v19, v18, s[8:9] offset:16
; __global__ void __launch_bounds__(NTHR, 2) k_main(Args a) {
;     ...
;             for (int q = 0; q < 4; ++q) { const int rr = rr0 + q, which = rr >> 14, row = rr & 16383;
;                 float ss = 0.f;
; #pragma unroll
;                 for (int jq = 0; jq < 4; ++jq) ss += v[q][jq].x * v[q][jq].x + v[q][jq].y * v[q][jq].y + v[q][jq].z * v[q][jq].z + v[q][jq].w * v[q][jq].w;
;                 ss = wave_sum(ss);
;                 const float step = ss > 0.f ? 0.335f * sqrtf(ss * (1.f / D)) : 1.f, inv = 1.f / step;
;                 unsigned short* dst = (unsigned short*)((which ? V8 : U8) + (size_t)row * 128) + lane;
; #pragma unroll
;                 for (int jq = 0; jq < 4; ++jq) { const float e4[4] = {v[q][jq].x, v[q][jq].y, v[q][jq].z, v[q][jq].w}; unsigned w4 = 0u;
; #pragma unroll
;                     for (int i = 0; i < 4; ++i) { const int qi = (int)fminf(fmaxf(floorf(e4[i] * inv), -8.f), 7.f); w4 |= ((unsigned)qi & 15u) << (4 * i); }
;                     dst[(size_t)jq * (16384 * 64)] = (unsigned short)w4; }
;                 if (lane == 0) (which ? SV : SU)[row] = 0.5f * step;
.LBB0_133:
	s_or_b64 exec, exec, s[0:1]
	v_mov_b32_e32 v20, v15
	v_mov_b32_e32 v21, v11
	v_mov_b32_e32 v18, v14
	v_mov_b32_e32 v19, v10
	v_pk_mul_f32 v[20:21], v[20:21], v[20:21]
	v_mov_b32_e32 v22, v16
	v_mov_b32_e32 v23, v12
	v_pk_fma_f32 v[18:19], v[18:19], v[18:19], v[20:21]
	v_mov_b32_e32 v24, v17
	v_pk_fma_f32 v[18:19], v[22:23], v[22:23], v[18:19]
	v_mov_b32_e32 v22, v7
	s_waitcnt vmcnt(12)
	v_mov_b32_e32 v23, v3
	v_mov_b32_e32 v25, v13
	v_mov_b32_e32 v20, v6
	v_mov_b32_e32 v21, v2
	v_pk_mul_f32 v[22:23], v[22:23], v[22:23]
	v_pk_fma_f32 v[18:19], v[24:25], v[24:25], v[18:19]
	v_mov_b32_e32 v24, v8
	v_mov_b32_e32 v25, v4
	v_pk_fma_f32 v[20:21], v[20:21], v[20:21], v[22:23]
	v_mov_b32_e32 v26, v9
	v_mov_b32_e32 v27, v5
	v_pk_fma_f32 v[20:21], v[24:25], v[24:25], v[20:21]
	v_add_f32_e32 v18, v18, v19
	v_pk_fma_f32 v[20:21], v[26:27], v[26:27], v[20:21]
	s_or_b32 s6, s6, 0x180
	v_add_f32_e32 v18, v18, v20
	v_add_f32_e32 v18, v18, v21
	s_nop 1
	v_add_f32_dpp v18, v18, v18 quad_perm:[1,0,3,2] row_mask:0xf bank_mask:0xf bound_ctrl:1
	s_nop 1
	v_add_f32_dpp v18, v18, v18 quad_perm:[2,3,0,1] row_mask:0xf bank_mask:0xf bound_ctrl:1
	s_nop 1
	v_add_f32_dpp v18, v18, v18 row_half_mirror row_mask:0xf bank_mask:0xf bound_ctrl:1
	s_nop 1
	v_add_f32_dpp v18, v18, v18 row_mirror row_mask:0xf bank_mask:0xf bound_ctrl:1
	s_nop 0
	v_readlane_b32 s23, v18, 16
	v_readlane_b32 s24, v18, 48
	v_readlane_b32 s0, v18, 0
	v_readlane_b32 s1, v18, 32
	v_mov_b32_e32 v18, s23
	v_mov_b32_e32 v19, s24
	v_pk_add_f32 v[18:19], s[0:1], v[18:19]
	s_nop 0
	v_add_f32_e32 v18, v18, v19
	v_mul_f32_e32 v19, 0x3a800000, v18
	v_mul_f32_e32 v20, 0x4f800000, v19
	v_cmp_gt_f32_e32 vcc, s16, v19
	s_nop 1
	v_cndmask_b32_e32 v19, v19, v20, vcc
	v_sqrt_f32_e32 v20, v19
	s_nop 0
	v_add_u32_e32 v21, -1, v20
	v_fma_f32 v22, -v21, v20, v19
	v_cmp_ge_f32_e64 s[0:1], 0, v22
	v_add_u32_e32 v22, 1, v20
	s_nop 0
	v_cndmask_b32_e64 v21, v20, v21, s[0:1]
	v_fma_f32 v20, -v22, v20, v19
	v_cmp_lt_f32_e64 s[0:1], 0, v20
	s_nop 1
	v_cndmask_b32_e64 v20, v21, v22, s[0:1]
	v_mul_f32_e32 v21, 0x37800000, v20
	v_cndmask_b32_e32 v20, v20, v21, vcc
	v_cmp_class_f32_e32 vcc, v19, v63
	s_nop 1
	v_cndmask_b32_e32 v19, v20, v19, vcc
	v_mul_f32_e32 v19, 0x3eab851f, v19
	v_cmp_lt_f32_e32 vcc, 0, v18
	s_nop 1
	v_cndmask_b32_e32 v18, 1.0, v19, vcc
	v_div_scale_f32 v19, s[0:1], v18, v18, 1.0
	v_rcp_f32_e32 v20, v19
	s_nop 0
	v_fma_f32 v21, -v19, v20, 1.0
	v_fmac_f32_e32 v20, v21, v20
	v_div_scale_f32 v21, vcc, 1.0, v18, 1.0
	v_mul_f32_e32 v22, v21, v20
	v_fma_f32 v23, -v19, v22, v21
	v_fmac_f32_e32 v22, v23, v20
	v_fma_f32 v19, -v19, v22, v21
	v_div_fmas_f32 v19, v19, v20, v22
	v_div_fixup_f32 v19, v19, v18, 1.0
	v_mul_f32_e32 v10, v19, v10
	v_mul_f32_e32 v11, v19, v11
	v_floor_f32_e32 v10, v10
	v_floor_f32_e32 v11, v11
	v_mul_f32_e32 v12, v19, v12
	v_med3_f32 v10, v10, s17, v70
	v_med3_f32 v11, v11, s17, v70
	v_floor_f32_e32 v12, v12
	v_cvt_i32_f32_e32 v10, v10
	v_cvt_i32_f32_e32 v11, v11
	v_med3_f32 v12, v12, s17, v70
	v_cvt_i32_f32_e32 v12, v12
	v_mul_f32_e32 v6, v19, v6
	v_and_b32_e32 v10, 15, v10
	v_lshlrev_b32_e32 v11, 4, v11
	v_floor_f32_e32 v6, v6
	v_mul_f32_e32 v13, v19, v13
	v_and_or_b32 v10, v11, s18, v10
	v_lshlrev_b32_e32 v11, 8, v12
	v_med3_f32 v6, v6, s17, v70
	v_floor_f32_e32 v13, v13
	v_and_or_b32 v10, v11, s19, v10
	v_cvt_i32_f32_e32 v11, v6
	v_mul_f32_e32 v6, v19, v7
	v_med3_f32 v13, v13, s17, v70
	v_floor_f32_e32 v6, v6
	v_mul_f32_e32 v8, v19, v8
	v_cvt_i32_f32_e32 v13, v13
	v_med3_f32 v6, v6, s17, v70
	v_floor_f32_e32 v8, v8
	v_cvt_i32_f32_e32 v12, v6
	v_med3_f32 v8, v8, s17, v70
	v_lshl_add_u64 v[20:21], v[68:69], 0, s[6:7]
	v_mul_f32_e32 v14, v19, v14
	v_mul_f32_e32 v15, v19, v15
	v_cvt_i32_f32_e32 v8, v8
	v_floor_f32_e32 v14, v14
	v_floor_f32_e32 v15, v15
	v_mul_f32_e32 v16, v19, v16
	v_add_co_u32_e32 v6, vcc, s20, v20
	v_med3_f32 v14, v14, s17, v70
	v_med3_f32 v15, v15, s17, v70
	v_floor_f32_e32 v16, v16
	v_lshl_or_b32 v10, v13, 12, v10
	v_addc_co_u32_e32 v7, vcc, 0, v21, vcc
	v_mul_f32_e32 v2, v19, v2
	v_cvt_i32_f32_e32 v14, v14
	v_cvt_i32_f32_e32 v15, v15
	v_med3_f32 v16, v16, s17, v70
	v_mov_b32_e32 v237, v10
	v_and_b32_e32 v6, 15, v11
	v_lshlrev_b32_e32 v7, 4, v12
	v_floor_f32_e32 v2, v2
	v_cvt_i32_f32_e32 v16, v16
	v_mul_f32_e32 v9, v19, v9
	v_and_or_b32 v6, v7, s18, v6
	v_lshlrev_b32_e32 v7, 8, v8
	v_med3_f32 v2, v2, s17, v70
	v_floor_f32_e32 v9, v9
	v_and_or_b32 v6, v7, s19, v6
	v_cvt_i32_f32_e32 v7, v2
	v_mul_f32_e32 v2, v19, v3
	v_med3_f32 v9, v9, s17, v70
	v_floor_f32_e32 v2, v2
	v_mul_f32_e32 v4, v19, v4
	v_and_b32_e32 v14, 15, v14
	v_lshlrev_b32_e32 v15, 4, v15
	v_cvt_i32_f32_e32 v9, v9
	v_med3_f32 v2, v2, s17, v70
	v_floor_f32_e32 v4, v4
	v_and_or_b32 v14, v15, s18, v14
	v_lshlrev_b32_e32 v15, 8, v16
	v_cvt_i32_f32_e32 v8, v2
	v_med3_f32 v4, v4, s17, v70
	v_mul_f32_e32 v5, v19, v5
	v_and_or_b32 v14, v15, s19, v14
	v_mul_f32_e32 v15, v19, v17
	v_cvt_i32_f32_e32 v4, v4
	v_floor_f32_e32 v5, v5
	v_floor_f32_e32 v15, v15
	v_add_co_u32_e32 v2, vcc, s21, v20
	v_med3_f32 v5, v5, s17, v70
	v_med3_f32 v15, v15, s17, v70
	v_lshl_or_b32 v6, v9, 12, v6
	v_addc_co_u32_e32 v3, vcc, 0, v21, vcc
	v_cvt_i32_f32_e32 v5, v5
	v_cvt_i32_f32_e32 v15, v15
	v_mov_b32_e32 v238, v6
	v_and_b32_e32 v2, 15, v7
	v_lshlrev_b32_e32 v3, 4, v8
	v_and_or_b32 v2, v3, s18, v2
	v_lshlrev_b32_e32 v3, 8, v4
	v_and_or_b32 v2, v3, s19, v2
	v_lshl_or_b32 v4, v5, 12, v2
	v_add_co_u32_e32 v2, vcc, 0x600000, v20
	v_lshl_or_b32 v14, v15, 12, v14
	s_nop 0
	v_addc_co_u32_e32 v3, vcc, 0, v21, vcc
	v_mov_b32_e32 v236, v14
	v_mov_b32_e32 v239, v4
	v_cndmask_b32_e64 v240, v237, v236, s[44:45]
	v_cndmask_b32_e64 v241, v239, v238, s[44:45]
	s_nop 1
	v_mov_b32_dpp v242, v240 quad_perm:[1,0,3,2] row_mask:0xf bank_mask:0xf
	v_mov_b32_dpp v243, v241 quad_perm:[1,0,3,2] row_mask:0xf bank_mask:0xf
	v_cndmask_b32_e64 v236, v236, v242, s[44:45]
	v_cndmask_b32_e64 v237, v242, v237, s[44:45]
	v_cndmask_b32_e64 v238, v238, v243, s[44:45]
	v_cndmask_b32_e64 v239, v243, v239, s[44:45]
	v_cndmask_b32_e64 v240, v238, v236, s[46:47]
	v_cndmask_b32_e64 v241, v239, v237, s[46:47]
	s_nop 1
	v_mov_b32_dpp v242, v240 quad_perm:[2,3,0,1] row_mask:0xf bank_mask:0xf
	v_mov_b32_dpp v243, v241 quad_perm:[2,3,0,1] row_mask:0xf bank_mask:0xf
	v_cndmask_b32_e64 v236, v236, v242, s[46:47]
	v_cndmask_b32_e64 v238, v242, v238, s[46:47]
	v_cndmask_b32_e64 v237, v237, v243, s[46:47]
	v_cndmask_b32_e64 v239, v243, v239, s[46:47]
	v_perm_b32 v248, v237, v236, s48
	v_perm_b32 v249, v239, v238, s48
	v_lshl_add_u64 v[246:247], v[20:21], 0, v[244:245]
	global_store_dwordx2 v[246:247], v[248:249], off
	s_and_saveexec_b64 s[0:1], s[4:5]
	s_cbranch_execz .LBB0_126
	s_lshl_b32 s6, s22, 3
	v_mul_f32_e32 v2, 0.5, v18
	v_mov_b32_e32 v3, s6
	global_store_dword v3, v2, s[8:9] offset:24
	s_branch .LBB0_126

; #define LAS __attribute__((address_space(3)))
; __global__ void __launch_bounds__(NTHR, 2) k_main(Args a) {
;     ...
;             for (int it = 0; it < 8; ++it) {
;                 const int tl = it * 8 + wave, t = j * 64 + tl;
;                 const unsigned ew = *(const LAS unsigned*)(EL + tl * 128 + 2 * lane); const int e0 = (int)(ew & 0xffffu), e1 = (int)(ew >> 16);
;                 typedef int i2v __attribute__((ext_vector_type(2))); const i2v si = *(const LAS i2v*)(ACC + tl * 128 + 2 * lane);
;                 typedef float f2v __attribute__((ext_vector_type(2))); const f2v gt = *(const LAS f2v*)(GL + tl * 128 + 2 * lane); const float xs = XS[t];
;                 const int sx = ((const int*)(XS + T))[t];
;                 const float z0 = (float)(2 * si.x + sx) * SU[e0] * xs, z1 = (float)(2 * si.y + sx) * SU[e1] * xs;
.LBB0_674:
	s_ashr_i32 s41, s40, 31
	s_lshl_b64 s[10:11], s[40:41], 2
	s_add_u32 s14, s90, s10
	s_addc_u32 s15, s91, s11
	v_readlane_b32 s42, v235, 36
	v_readlane_b32 s43, v235, 37
	v_add_u32_e32 v74, 0x16000, v91
	v_mov_b32_e32 v77, 3
	ds_read_b32 v18, v92
	ds_read_b32 v19, v92 offset:2048
	ds_read_b32 v20, v92 offset:4096
	ds_read_b32 v21, v92 offset:6144
	ds_read_b32 v22, v92 offset:8192
	ds_read_b32 v23, v92 offset:10240
	ds_read_b32 v24, v92 offset:12288
	ds_read_b32 v25, v92 offset:14336
	ds_read_b64 v[26:27], v91
	ds_read_b64 v[42:43], v74
	ds_read_b64 v[28:29], v91 offset:4096
	ds_read_b64 v[44:45], v74 offset:4096
	ds_read_b64 v[30:31], v91 offset:8192
	ds_read_b64 v[46:47], v74 offset:8192
	ds_read_b64 v[32:33], v91 offset:12288
	ds_read_b64 v[48:49], v74 offset:12288
	ds_read_b64 v[34:35], v91 offset:16384
	ds_read_b64 v[50:51], v74 offset:16384
	ds_read_b64 v[36:37], v91 offset:20480
	ds_read_b64 v[52:53], v74 offset:20480
	ds_read_b64 v[38:39], v91 offset:24576
	ds_read_b64 v[54:55], v74 offset:24576
	ds_read_b64 v[40:41], v91 offset:28672
	ds_read_b64 v[56:57], v74 offset:28672
	global_load_dword v58, v109, s[14:15]
	global_load_dword v66, v108, s[14:15]
	global_load_dword v59, v109, s[14:15] offset:32
	global_load_dword v67, v108, s[14:15] offset:32
	global_load_dword v60, v109, s[14:15] offset:64
	global_load_dword v68, v108, s[14:15] offset:64
	global_load_dword v61, v109, s[14:15] offset:96
	global_load_dword v69, v108, s[14:15] offset:96
	global_load_dword v62, v109, s[14:15] offset:128
	global_load_dword v70, v108, s[14:15] offset:128
	global_load_dword v63, v109, s[14:15] offset:160
	global_load_dword v71, v108, s[14:15] offset:160
	global_load_dword v64, v109, s[14:15] offset:192
	global_load_dword v72, v108, s[14:15] offset:192
	global_load_dword v65, v109, s[14:15] offset:224
	global_load_dword v73, v108, s[14:15] offset:224
	s_waitcnt lgkmcnt(0)
	v_lshlrev_b32_sdwa v75, v77, v18 dst_sel:DWORD dst_unused:UNUSED_PAD src0_sel:DWORD src1_sel:WORD_0
	v_lshlrev_b32_sdwa v76, v77, v18 dst_sel:DWORD dst_unused:UNUSED_PAD src0_sel:DWORD src1_sel:WORD_1
	s_nop 1
	global_load_dwordx2 v[122:123], v75, s[42:43]
	global_load_dwordx2 v[138:139], v76, s[42:43]
	v_lshlrev_b32_sdwa v75, v77, v19 dst_sel:DWORD dst_unused:UNUSED_PAD src0_sel:DWORD src1_sel:WORD_0
	v_lshlrev_b32_sdwa v76, v77, v19 dst_sel:DWORD dst_unused:UNUSED_PAD src0_sel:DWORD src1_sel:WORD_1
	s_nop 1
	global_load_dwordx2 v[124:125], v75, s[42:43]
	global_load_dwordx2 v[140:141], v76, s[42:43]
	v_lshlrev_b32_sdwa v75, v77, v20 dst_sel:DWORD dst_unused:UNUSED_PAD src0_sel:DWORD src1_sel:WORD_0
	v_lshlrev_b32_sdwa v76, v77, v20 dst_sel:DWORD dst_unused:UNUSED_PAD src0_sel:DWORD src1_sel:WORD_1
	s_nop 1
	global_load_dwordx2 v[126:127], v75, s[42:43]
	global_load_dwordx2 v[142:143], v76, s[42:43]
	v_lshlrev_b32_sdwa v75, v77, v21 dst_sel:DWORD dst_unused:UNUSED_PAD src0_sel:DWORD src1_sel:WORD_0
	v_lshlrev_b32_sdwa v76, v77, v21 dst_sel:DWORD dst_unused:UNUSED_PAD src0_sel:DWORD src1_sel:WORD_1
	s_nop 1
	global_load_dwordx2 v[128:129], v75, s[42:43]
	global_load_dwordx2 v[144:145], v76, s[42:43]
	v_lshlrev_b32_sdwa v75, v77, v22 dst_sel:DWORD dst_unused:UNUSED_PAD src0_sel:DWORD src1_sel:WORD_0
	v_lshlrev_b32_sdwa v76, v77, v22 dst_sel:DWORD dst_unused:UNUSED_PAD src0_sel:DWORD src1_sel:WORD_1
	s_nop 1
	global_load_dwordx2 v[130:131], v75, s[42:43]
	global_load_dwordx2 v[146:147], v76, s[42:43]
	v_lshlrev_b32_sdwa v75, v77, v23 dst_sel:DWORD dst_unused:UNUSED_PAD src0_sel:DWORD src1_sel:WORD_0
	v_lshlrev_b32_sdwa v76, v77, v23 dst_sel:DWORD dst_unused:UNUSED_PAD src0_sel:DWORD src1_sel:WORD_1
	s_nop 1
	global_load_dwordx2 v[132:133], v75, s[42:43]
	global_load_dwordx2 v[148:149], v76, s[42:43]
	v_lshlrev_b32_sdwa v75, v77, v24 dst_sel:DWORD dst_unused:UNUSED_PAD src0_sel:DWORD src1_sel:WORD_0
	v_lshlrev_b32_sdwa v76, v77, v24 dst_sel:DWORD dst_unused:UNUSED_PAD src0_sel:DWORD src1_sel:WORD_1
	s_nop 1
	global_load_dwordx2 v[134:135], v75, s[42:43]
	global_load_dwordx2 v[150:151], v76, s[42:43]
	v_lshlrev_b32_sdwa v75, v77, v25 dst_sel:DWORD dst_unused:UNUSED_PAD src0_sel:DWORD src1_sel:WORD_0
	v_lshlrev_b32_sdwa v76, v77, v25 dst_sel:DWORD dst_unused:UNUSED_PAD src0_sel:DWORD src1_sel:WORD_1
	s_nop 1
	global_load_dwordx2 v[136:137], v75, s[42:43]
	global_load_dwordx2 v[152:153], v76, s[42:43]
	s_waitcnt vmcnt(14)
; #define LAS __attribute__((address_space(3)))
; __global__ void __launch_bounds__(NTHR, 2) k_main(Args a) {
;     ...
;                 const unsigned ew = *(const LAS unsigned*)(EL + tl * 128 + 2 * lane); const int e0 = (int)(ew & 0xffffu), e1 = (int)(ew >> 16);
;                 typedef int i2v __attribute__((ext_vector_type(2))); const i2v si = *(const LAS i2v*)(ACC + tl * 128 + 2 * lane);
;                 typedef float f2v __attribute__((ext_vector_type(2))); const f2v gt = *(const LAS f2v*)(GL + tl * 128 + 2 * lane); const float xs = XS[t];
;                 const int sx = ((const int*)(XS + T))[t];
;                 const float z0 = (float)(2 * si.x + sx) * SU[e0] * xs, z1 = (float)(2 * si.y + sx) * SU[e1] * xs;
;                 const float a0 = gt.x * gelu_as(z0) * SV[e0], a1 = gt.y * gelu_as(z1) * SV[e1];
;                 const float mx = wave_max_dpp(fmaxf(fabsf(a0), fabsf(a1)));
;                 const float sc = mx > 0.f ? mx * (1.f / 119.f) : 1.f, inv = 1.f / sc;
;                 const int q0 = (int)rintf(a0 * inv), q1 = (int)rintf(a1 * inv);
;                 *(LAS unsigned short*)(AL + tl * 128 + 2 * lane) = (unsigned short)((q0 & 255) | ((q1 & 255) << 8));
;                 const int qs = wave_sum_dpp_i(q0 + q1);
;                 if (lane == 0) { ASC[tl] = sc; SAL[tl] = qs; }
	v_lshl_add_u32 v154, v26, 1, v58
	v_lshl_add_u32 v155, v27, 1, v58
	v_cvt_f32_i32_e32 v154, v154
	v_cvt_f32_i32_e32 v155, v155
	v_mul_f32_e32 v154, v122, v154
	v_mul_f32_e32 v155, v138, v155
	v_mul_f32_e32 v154, v66, v154
	v_mul_f32_e32 v155, v66, v155
	v_mul_f32_e64 v156, |v154|, s82
	v_mul_f32_e64 v157, |v155|, s82
	v_fma_f32 v158, v156, s83, 1.0
	v_fma_f32 v159, v157, s83, 1.0
	v_rcp_f32_e32 v158, v158
	v_rcp_f32_e32 v159, v159
	v_mul_f32_e64 v156, v156, -v156
	v_mul_f32_e64 v157, v157, -v157
	v_mul_f32_e32 v156, 0x3fb8aa3b, v156
	v_mul_f32_e32 v157, 0x3fb8aa3b, v157
	v_fmamk_f32 v160, v158, 0x3f87dc22, v110
	v_fmamk_f32 v161, v159, 0x3f87dc22, v110
	v_exp_f32_e32 v156, v156
	v_exp_f32_e32 v157, v157
	v_fmaak_f32 v160, v158, v160, 0x3fb5f0e3
	v_fmaak_f32 v161, v159, v161, 0x3fb5f0e3
	v_fmaak_f32 v160, v158, v160, 0xbe91a98e
	v_fmaak_f32 v161, v159, v161, 0xbe91a98e
	v_fmaak_f32 v160, v158, v160, 0x3e827906
	v_fmaak_f32 v161, v159, v161, 0x3e827906
	v_mul_f32_e32 v158, v158, v160
	v_mul_f32_e32 v159, v159, v161
	v_fma_f32 v156, -v156, v158, 1.0
	v_fma_f32 v157, -v157, v159, 1.0
	v_mul_f32_e32 v162, 0.5, v154
	v_mul_f32_e32 v163, 0.5, v155
	v_bfi_b32 v154, s84, v156, v154
	v_bfi_b32 v155, s84, v157, v155
	v_add_f32_e32 v154, 1.0, v154
	v_add_f32_e32 v155, 1.0, v155
	v_mul_f32_e32 v154, v162, v154
	v_mul_f32_e32 v155, v163, v155
	v_mul_f32_e32 v154, v42, v154
	v_mul_f32_e32 v155, v43, v155
	v_mul_f32_e32 v154, v123, v154
	v_mul_f32_e32 v155, v139, v155
	v_max_f32_e64 v164, |v154|, |v155|
	s_nop 1
	v_max_f32_dpp v164, v164, v164 quad_perm:[1,0,3,2] row_mask:0xf bank_mask:0xf
	s_nop 1
	v_max_f32_dpp v164, v164, v164 quad_perm:[2,3,0,1] row_mask:0xf bank_mask:0xf
	s_nop 1
	v_max_f32_dpp v164, v164, v164 row_half_mirror row_mask:0xf bank_mask:0xf
	s_nop 1
	v_max_f32_dpp v164, v164, v164 row_mirror row_mask:0xf bank_mask:0xf
	s_nop 1
	v_readlane_b32 s46, v164, 32
	v_readlane_b32 s47, v164, 48
	v_readlane_b32 s12, v164, 0
	v_readlane_b32 s13, v164, 16
	s_nop 1
	v_mov_b32_e32 v164, s47
	v_max_f32_e32 v164, s46, v164
	v_mov_b32_e32 v165, s13
	v_max3_f32 v164, s12, v165, v164
	v_mul_f32_e32 v165, 0x3c09ae41, v164
	v_cmp_lt_f32_e32 vcc, 0, v164
	s_nop 1
	v_cndmask_b32_e32 v164, 1.0, v165, vcc
	v_div_scale_f32 v166, s[12:13], v164, v164, 1.0
	v_rcp_f32_e32 v167, v166
	v_div_scale_f32 v168, vcc, 1.0, v164, 1.0
	v_fma_f32 v169, -v166, v167, 1.0
	v_fmac_f32_e32 v167, v169, v167
	v_mul_f32_e32 v169, v168, v167
	v_fma_f32 v170, -v166, v169, v168
	v_fmac_f32_e32 v169, v170, v167
	v_fma_f32 v166, -v166, v169, v168
	v_div_fmas_f32 v166, v166, v167, v169
	v_div_fixup_f32 v166, v166, v164, 1.0
	v_mul_f32_e32 v154, v166, v154
	v_mul_f32_e32 v155, v166, v155
	v_rndne_f32_e32 v154, v154
	v_rndne_f32_e32 v155, v155
	v_cvt_i32_f32_e32 v154, v154
	v_cvt_i32_f32_e32 v155, v155
	v_perm_b32 v167, v155, v154, s85
	v_add_u32_e32 v154, v154, v155
	ds_write_b16 v90, v167
	s_nop 1
	v_add_u32_dpp v154, v154, v154 quad_perm:[1,0,3,2] row_mask:0xf bank_mask:0xf bound_ctrl:1
	s_nop 1
	v_add_u32_dpp v154, v154, v154 quad_perm:[2,3,0,1] row_mask:0xf bank_mask:0xf bound_ctrl:1
	s_nop 1
	v_add_u32_dpp v154, v154, v154 row_half_mirror row_mask:0xf bank_mask:0xf bound_ctrl:1
	s_nop 1
	v_add_u32_dpp v154, v154, v154 row_mirror row_mask:0xf bank_mask:0xf bound_ctrl:1
	s_nop 1
	v_readlane_b32 s46, v154, 0
	v_readlane_b32 s47, v154, 16
	v_readlane_b32 s12, v154, 32
	v_readlane_b32 s13, v154, 48
	s_nop 1
	s_add_i32 s46, s47, s46
	s_add_i32 s46, s46, s12
	s_add_i32 s46, s46, s13
	s_mov_b32 s47, s67
	s_and_saveexec_b64 s[12:13], s[8:9]
	v_mov_b32_e32 v154, s47
	v_mov_b32_e32 v155, s46
	ds_write2st64_b32 v154, v164, v155 offset1:1
	s_or_b64 exec, exec, s[12:13]
	s_waitcnt vmcnt(12)
	v_lshl_add_u32 v154, v28, 1, v59
	v_lshl_add_u32 v155, v29, 1, v59
	v_cvt_f32_i32_e32 v154, v154
	v_cvt_f32_i32_e32 v155, v155
	v_mul_f32_e32 v154, v124, v154
	v_mul_f32_e32 v155, v140, v155
	v_mul_f32_e32 v154, v67, v154
	v_mul_f32_e32 v155, v67, v155
	v_mul_f32_e64 v156, |v154|, s82
	v_mul_f32_e64 v157, |v155|, s82
	v_fma_f32 v158, v156, s83, 1.0
	v_fma_f32 v159, v157, s83, 1.0
	v_rcp_f32_e32 v158, v158
	v_rcp_f32_e32 v159, v159
	v_mul_f32_e64 v156, v156, -v156
	v_mul_f32_e64 v157, v157, -v157
	v_mul_f32_e32 v156, 0x3fb8aa3b, v156
	v_mul_f32_e32 v157, 0x3fb8aa3b, v157
	v_fmamk_f32 v160, v158, 0x3f87dc22, v110
	v_fmamk_f32 v161, v159, 0x3f87dc22, v110
	v_exp_f32_e32 v156, v156
	v_exp_f32_e32 v157, v157
	v_fmaak_f32 v160, v158, v160, 0x3fb5f0e3
	v_fmaak_f32 v161, v159, v161, 0x3fb5f0e3
	v_fmaak_f32 v160, v158, v160, 0xbe91a98e
	v_fmaak_f32 v161, v159, v161, 0xbe91a98e
	v_fmaak_f32 v160, v158, v160, 0x3e827906
	v_fmaak_f32 v161, v159, v161, 0x3e827906
	v_mul_f32_e32 v158, v158, v160
	v_mul_f32_e32 v159, v159, v161
	v_fma_f32 v156, -v156, v158, 1.0
	v_fma_f32 v157, -v157, v159, 1.0
	v_mul_f32_e32 v162, 0.5, v154
	v_mul_f32_e32 v163, 0.5, v155
	v_bfi_b32 v154, s84, v156, v154
	v_bfi_b32 v155, s84, v157, v155
	v_add_f32_e32 v154, 1.0, v154
	v_add_f32_e32 v155, 1.0, v155
	v_mul_f32_e32 v154, v162, v154
	v_mul_f32_e32 v155, v163, v155
	v_mul_f32_e32 v154, v44, v154
	v_mul_f32_e32 v155, v45, v155
	v_mul_f32_e32 v154, v125, v154
	v_mul_f32_e32 v155, v141, v155
	v_max_f32_e64 v164, |v154|, |v155|
	s_nop 1
	v_max_f32_dpp v164, v164, v164 quad_perm:[1,0,3,2] row_mask:0xf bank_mask:0xf
	s_nop 1
	v_max_f32_dpp v164, v164, v164 quad_perm:[2,3,0,1] row_mask:0xf bank_mask:0xf
	s_nop 1
	v_max_f32_dpp v164, v164, v164 row_half_mirror row_mask:0xf bank_mask:0xf
	s_nop 1
	v_max_f32_dpp v164, v164, v164 row_mirror row_mask:0xf bank_mask:0xf
	s_nop 1
	v_readlane_b32 s46, v164, 32
	v_readlane_b32 s47, v164, 48
	v_readlane_b32 s12, v164, 0
; #define LAS __attribute__((address_space(3)))
; __global__ void __launch_bounds__(NTHR, 2) k_main(Args a) {
;     ...
;                 const unsigned ew = *(const LAS unsigned*)(EL + tl * 128 + 2 * lane); const int e0 = (int)(ew & 0xffffu), e1 = (int)(ew >> 16);
;                 typedef int i2v __attribute__((ext_vector_type(2))); const i2v si = *(const LAS i2v*)(ACC + tl * 128 + 2 * lane);
;                 typedef float f2v __attribute__((ext_vector_type(2))); const f2v gt = *(const LAS f2v*)(GL + tl * 128 + 2 * lane); const float xs = XS[t];
;                 const int sx = ((const int*)(XS + T))[t];
;                 const float z0 = (float)(2 * si.x + sx) * SU[e0] * xs, z1 = (float)(2 * si.y + sx) * SU[e1] * xs;
;                 const float a0 = gt.x * gelu_as(z0) * SV[e0], a1 = gt.y * gelu_as(z1) * SV[e1];
;                 const float mx = wave_max_dpp(fmaxf(fabsf(a0), fabsf(a1)));
;                 const float sc = mx > 0.f ? mx * (1.f / 119.f) : 1.f, inv = 1.f / sc;
;                 const int q0 = (int)rintf(a0 * inv), q1 = (int)rintf(a1 * inv);
;                 *(LAS unsigned short*)(AL + tl * 128 + 2 * lane) = (unsigned short)((q0 & 255) | ((q1 & 255) << 8));
;                 const int qs = wave_sum_dpp_i(q0 + q1);
;                 if (lane == 0) { ASC[tl] = sc; SAL[tl] = qs; }
	v_readlane_b32 s13, v164, 16
	s_nop 1
	v_mov_b32_e32 v164, s47
	v_max_f32_e32 v164, s46, v164
	v_mov_b32_e32 v165, s13
	v_max3_f32 v164, s12, v165, v164
	v_mul_f32_e32 v165, 0x3c09ae41, v164
	v_cmp_lt_f32_e32 vcc, 0, v164
	s_nop 1
	v_cndmask_b32_e32 v164, 1.0, v165, vcc
	v_div_scale_f32 v166, s[12:13], v164, v164, 1.0
	v_rcp_f32_e32 v167, v166
	v_div_scale_f32 v168, vcc, 1.0, v164, 1.0
	v_fma_f32 v169, -v166, v167, 1.0
	v_fmac_f32_e32 v167, v169, v167
	v_mul_f32_e32 v169, v168, v167
	v_fma_f32 v170, -v166, v169, v168
	v_fmac_f32_e32 v169, v170, v167
	v_fma_f32 v166, -v166, v169, v168
	v_div_fmas_f32 v166, v166, v167, v169
	v_div_fixup_f32 v166, v166, v164, 1.0
	v_mul_f32_e32 v154, v166, v154
	v_mul_f32_e32 v155, v166, v155
	v_rndne_f32_e32 v154, v154
	v_rndne_f32_e32 v155, v155
	v_cvt_i32_f32_e32 v154, v154
	v_cvt_i32_f32_e32 v155, v155
	v_perm_b32 v167, v155, v154, s85
	v_add_u32_e32 v154, v154, v155
	ds_write_b16 v90, v167 offset:1024
	s_nop 1
	v_add_u32_dpp v154, v154, v154 quad_perm:[1,0,3,2] row_mask:0xf bank_mask:0xf bound_ctrl:1
	s_nop 1
	v_add_u32_dpp v154, v154, v154 quad_perm:[2,3,0,1] row_mask:0xf bank_mask:0xf bound_ctrl:1
	s_nop 1
	v_add_u32_dpp v154, v154, v154 row_half_mirror row_mask:0xf bank_mask:0xf bound_ctrl:1
	s_nop 1
	v_add_u32_dpp v154, v154, v154 row_mirror row_mask:0xf bank_mask:0xf bound_ctrl:1
	s_nop 1
	v_readlane_b32 s46, v154, 0
	v_readlane_b32 s47, v154, 16
	v_readlane_b32 s12, v154, 32
	v_readlane_b32 s13, v154, 48
	s_nop 1
	s_add_i32 s46, s47, s46
	s_add_i32 s46, s46, s12
	s_add_i32 s46, s46, s13
	s_add_i32 s47, s67, 32
	s_and_saveexec_b64 s[12:13], s[8:9]
	v_mov_b32_e32 v154, s47
	v_mov_b32_e32 v155, s46
	ds_write2st64_b32 v154, v164, v155 offset1:1
	s_or_b64 exec, exec, s[12:13]
	s_waitcnt vmcnt(10)
	v_lshl_add_u32 v154, v30, 1, v60
	v_lshl_add_u32 v155, v31, 1, v60
	v_cvt_f32_i32_e32 v154, v154
	v_cvt_f32_i32_e32 v155, v155
	v_mul_f32_e32 v154, v126, v154
	v_mul_f32_e32 v155, v142, v155
	v_mul_f32_e32 v154, v68, v154
	v_mul_f32_e32 v155, v68, v155
	v_mul_f32_e64 v156, |v154|, s82
	v_mul_f32_e64 v157, |v155|, s82
	v_fma_f32 v158, v156, s83, 1.0
	v_fma_f32 v159, v157, s83, 1.0
	v_rcp_f32_e32 v158, v158
	v_rcp_f32_e32 v159, v159
	v_mul_f32_e64 v156, v156, -v156
	v_mul_f32_e64 v157, v157, -v157
	v_mul_f32_e32 v156, 0x3fb8aa3b, v156
	v_mul_f32_e32 v157, 0x3fb8aa3b, v157
	v_fmamk_f32 v160, v158, 0x3f87dc22, v110
	v_fmamk_f32 v161, v159, 0x3f87dc22, v110
	v_exp_f32_e32 v156, v156
	v_exp_f32_e32 v157, v157
	v_fmaak_f32 v160, v158, v160, 0x3fb5f0e3
	v_fmaak_f32 v161, v159, v161, 0x3fb5f0e3
	v_fmaak_f32 v160, v158, v160, 0xbe91a98e
	v_fmaak_f32 v161, v159, v161, 0xbe91a98e
	v_fmaak_f32 v160, v158, v160, 0x3e827906
	v_fmaak_f32 v161, v159, v161, 0x3e827906
	v_mul_f32_e32 v158, v158, v160
	v_mul_f32_e32 v159, v159, v161
	v_fma_f32 v156, -v156, v158, 1.0
	v_fma_f32 v157, -v157, v159, 1.0
	v_mul_f32_e32 v162, 0.5, v154
	v_mul_f32_e32 v163, 0.5, v155
	v_bfi_b32 v154, s84, v156, v154
	v_bfi_b32 v155, s84, v157, v155
	v_add_f32_e32 v154, 1.0, v154
	v_add_f32_e32 v155, 1.0, v155
	v_mul_f32_e32 v154, v162, v154
	v_mul_f32_e32 v155, v163, v155
	v_mul_f32_e32 v154, v46, v154
	v_mul_f32_e32 v155, v47, v155
	v_mul_f32_e32 v154, v127, v154
	v_mul_f32_e32 v155, v143, v155
	v_max_f32_e64 v164, |v154|, |v155|
	s_nop 1
	v_max_f32_dpp v164, v164, v164 quad_perm:[1,0,3,2] row_mask:0xf bank_mask:0xf
	s_nop 1
	v_max_f32_dpp v164, v164, v164 quad_perm:[2,3,0,1] row_mask:0xf bank_mask:0xf
	s_nop 1
	v_max_f32_dpp v164, v164, v164 row_half_mirror row_mask:0xf bank_mask:0xf
	s_nop 1
	v_max_f32_dpp v164, v164, v164 row_mirror row_mask:0xf bank_mask:0xf
	s_nop 1
	v_readlane_b32 s46, v164, 32
	v_readlane_b32 s47, v164, 48
	v_readlane_b32 s12, v164, 0
	v_readlane_b32 s13, v164, 16
	s_nop 1
	v_mov_b32_e32 v164, s47
	v_max_f32_e32 v164, s46, v164
	v_mov_b32_e32 v165, s13
	v_max3_f32 v164, s12, v165, v164
	v_mul_f32_e32 v165, 0x3c09ae41, v164
	v_cmp_lt_f32_e32 vcc, 0, v164
	s_nop 1
	v_cndmask_b32_e32 v164, 1.0, v165, vcc
	v_div_scale_f32 v166, s[12:13], v164, v164, 1.0
	v_rcp_f32_e32 v167, v166
	v_div_scale_f32 v168, vcc, 1.0, v164, 1.0
	v_fma_f32 v169, -v166, v167, 1.0
	v_fmac_f32_e32 v167, v169, v167
	v_mul_f32_e32 v169, v168, v167
	v_fma_f32 v170, -v166, v169, v168
	v_fmac_f32_e32 v169, v170, v167
	v_fma_f32 v166, -v166, v169, v168
	v_div_fmas_f32 v166, v166, v167, v169
	v_div_fixup_f32 v166, v166, v164, 1.0
	v_mul_f32_e32 v154, v166, v154
	v_mul_f32_e32 v155, v166, v155
	v_rndne_f32_e32 v154, v154
	v_rndne_f32_e32 v155, v155
	v_cvt_i32_f32_e32 v154, v154
	v_cvt_i32_f32_e32 v155, v155
	v_perm_b32 v167, v155, v154, s85
	v_add_u32_e32 v154, v154, v155
	ds_write_b16 v90, v167 offset:2048
	s_nop 1
	v_add_u32_dpp v154, v154, v154 quad_perm:[1,0,3,2] row_mask:0xf bank_mask:0xf bound_ctrl:1
	s_nop 1
	v_add_u32_dpp v154, v154, v154 quad_perm:[2,3,0,1] row_mask:0xf bank_mask:0xf bound_ctrl:1
	s_nop 1
	v_add_u32_dpp v154, v154, v154 row_half_mirror row_mask:0xf bank_mask:0xf bound_ctrl:1
	s_nop 1
	v_add_u32_dpp v154, v154, v154 row_mirror row_mask:0xf bank_mask:0xf bound_ctrl:1
	s_nop 1
	v_readlane_b32 s46, v154, 0
	v_readlane_b32 s47, v154, 16
	v_readlane_b32 s12, v154, 32
	v_readlane_b32 s13, v154, 48
	s_nop 1
	s_add_i32 s46, s47, s46
	s_add_i32 s46, s46, s12
	s_add_i32 s46, s46, s13
	s_add_i32 s47, s67, 64
	s_and_saveexec_b64 s[12:13], s[8:9]
	v_mov_b32_e32 v154, s47
	v_mov_b32_e32 v155, s46
	ds_write2st64_b32 v154, v164, v155 offset1:1
	s_or_b64 exec, exec, s[12:13]
	s_waitcnt vmcnt(8)
; #define LAS __attribute__((address_space(3)))
; __global__ void __launch_bounds__(NTHR, 2) k_main(Args a) {
;     ...
;                 const unsigned ew = *(const LAS unsigned*)(EL + tl * 128 + 2 * lane); const int e0 = (int)(ew & 0xffffu), e1 = (int)(ew >> 16);
;                 typedef int i2v __attribute__((ext_vector_type(2))); const i2v si = *(const LAS i2v*)(ACC + tl * 128 + 2 * lane);
;                 typedef float f2v __attribute__((ext_vector_type(2))); const f2v gt = *(const LAS f2v*)(GL + tl * 128 + 2 * lane); const float xs = XS[t];
;                 const int sx = ((const int*)(XS + T))[t];
;                 const float z0 = (float)(2 * si.x + sx) * SU[e0] * xs, z1 = (float)(2 * si.y + sx) * SU[e1] * xs;
;                 const float a0 = gt.x * gelu_as(z0) * SV[e0], a1 = gt.y * gelu_as(z1) * SV[e1];
;                 const float mx = wave_max_dpp(fmaxf(fabsf(a0), fabsf(a1)));
;                 const float sc = mx > 0.f ? mx * (1.f / 119.f) : 1.f, inv = 1.f / sc;
;                 const int q0 = (int)rintf(a0 * inv), q1 = (int)rintf(a1 * inv);
;                 *(LAS unsigned short*)(AL + tl * 128 + 2 * lane) = (unsigned short)((q0 & 255) | ((q1 & 255) << 8));
;                 const int qs = wave_sum_dpp_i(q0 + q1);
;                 if (lane == 0) { ASC[tl] = sc; SAL[tl] = qs; }
	v_lshl_add_u32 v154, v32, 1, v61
	v_lshl_add_u32 v155, v33, 1, v61
	v_cvt_f32_i32_e32 v154, v154
	v_cvt_f32_i32_e32 v155, v155
	v_mul_f32_e32 v154, v128, v154
	v_mul_f32_e32 v155, v144, v155
	v_mul_f32_e32 v154, v69, v154
	v_mul_f32_e32 v155, v69, v155
	v_mul_f32_e64 v156, |v154|, s82
	v_mul_f32_e64 v157, |v155|, s82
	v_fma_f32 v158, v156, s83, 1.0
	v_fma_f32 v159, v157, s83, 1.0
	v_rcp_f32_e32 v158, v158
	v_rcp_f32_e32 v159, v159
	v_mul_f32_e64 v156, v156, -v156
	v_mul_f32_e64 v157, v157, -v157
	v_mul_f32_e32 v156, 0x3fb8aa3b, v156
	v_mul_f32_e32 v157, 0x3fb8aa3b, v157
	v_fmamk_f32 v160, v158, 0x3f87dc22, v110
	v_fmamk_f32 v161, v159, 0x3f87dc22, v110
	v_exp_f32_e32 v156, v156
	v_exp_f32_e32 v157, v157
	v_fmaak_f32 v160, v158, v160, 0x3fb5f0e3
	v_fmaak_f32 v161, v159, v161, 0x3fb5f0e3
	v_fmaak_f32 v160, v158, v160, 0xbe91a98e
	v_fmaak_f32 v161, v159, v161, 0xbe91a98e
	v_fmaak_f32 v160, v158, v160, 0x3e827906
	v_fmaak_f32 v161, v159, v161, 0x3e827906
	v_mul_f32_e32 v158, v158, v160
	v_mul_f32_e32 v159, v159, v161
	v_fma_f32 v156, -v156, v158, 1.0
	v_fma_f32 v157, -v157, v159, 1.0
	v_mul_f32_e32 v162, 0.5, v154
	v_mul_f32_e32 v163, 0.5, v155
	v_bfi_b32 v154, s84, v156, v154
	v_bfi_b32 v155, s84, v157, v155
	v_add_f32_e32 v154, 1.0, v154
	v_add_f32_e32 v155, 1.0, v155
	v_mul_f32_e32 v154, v162, v154
	v_mul_f32_e32 v155, v163, v155
	v_mul_f32_e32 v154, v48, v154
	v_mul_f32_e32 v155, v49, v155
	v_mul_f32_e32 v154, v129, v154
	v_mul_f32_e32 v155, v145, v155
	v_max_f32_e64 v164, |v154|, |v155|
	s_nop 1
	v_max_f32_dpp v164, v164, v164 quad_perm:[1,0,3,2] row_mask:0xf bank_mask:0xf
	s_nop 1
	v_max_f32_dpp v164, v164, v164 quad_perm:[2,3,0,1] row_mask:0xf bank_mask:0xf
	s_nop 1
	v_max_f32_dpp v164, v164, v164 row_half_mirror row_mask:0xf bank_mask:0xf
	s_nop 1
	v_max_f32_dpp v164, v164, v164 row_mirror row_mask:0xf bank_mask:0xf
	s_nop 1
	v_readlane_b32 s46, v164, 32
	v_readlane_b32 s47, v164, 48
	v_readlane_b32 s12, v164, 0
	v_readlane_b32 s13, v164, 16
	s_nop 1
	v_mov_b32_e32 v164, s47
	v_max_f32_e32 v164, s46, v164
	v_mov_b32_e32 v165, s13
	v_max3_f32 v164, s12, v165, v164
	v_mul_f32_e32 v165, 0x3c09ae41, v164
	v_cmp_lt_f32_e32 vcc, 0, v164
	s_nop 1
	v_cndmask_b32_e32 v164, 1.0, v165, vcc
	v_div_scale_f32 v166, s[12:13], v164, v164, 1.0
	v_rcp_f32_e32 v167, v166
	v_div_scale_f32 v168, vcc, 1.0, v164, 1.0
	v_fma_f32 v169, -v166, v167, 1.0
	v_fmac_f32_e32 v167, v169, v167
	v_mul_f32_e32 v169, v168, v167
	v_fma_f32 v170, -v166, v169, v168
	v_fmac_f32_e32 v169, v170, v167
	v_fma_f32 v166, -v166, v169, v168
	v_div_fmas_f32 v166, v166, v167, v169
	v_div_fixup_f32 v166, v166, v164, 1.0
	v_mul_f32_e32 v154, v166, v154
	v_mul_f32_e32 v155, v166, v155
	v_rndne_f32_e32 v154, v154
	v_rndne_f32_e32 v155, v155
	v_cvt_i32_f32_e32 v154, v154
	v_cvt_i32_f32_e32 v155, v155
	v_perm_b32 v167, v155, v154, s85
	v_add_u32_e32 v154, v154, v155
	ds_write_b16 v90, v167 offset:3072
	s_nop 1
	v_add_u32_dpp v154, v154, v154 quad_perm:[1,0,3,2] row_mask:0xf bank_mask:0xf bound_ctrl:1
	s_nop 1
	v_add_u32_dpp v154, v154, v154 quad_perm:[2,3,0,1] row_mask:0xf bank_mask:0xf bound_ctrl:1
	s_nop 1
	v_add_u32_dpp v154, v154, v154 row_half_mirror row_mask:0xf bank_mask:0xf bound_ctrl:1
	s_nop 1
	v_add_u32_dpp v154, v154, v154 row_mirror row_mask:0xf bank_mask:0xf bound_ctrl:1
	s_nop 1
	v_readlane_b32 s46, v154, 0
	v_readlane_b32 s47, v154, 16
	v_readlane_b32 s12, v154, 32
	v_readlane_b32 s13, v154, 48
	s_nop 1
	s_add_i32 s46, s47, s46
	s_add_i32 s46, s46, s12
	s_add_i32 s46, s46, s13
	s_add_i32 s47, s67, 96
	s_and_saveexec_b64 s[12:13], s[8:9]
	v_mov_b32_e32 v154, s47
	v_mov_b32_e32 v155, s46
	ds_write2st64_b32 v154, v164, v155 offset1:1
	s_or_b64 exec, exec, s[12:13]
	s_waitcnt vmcnt(6)
	v_lshl_add_u32 v154, v34, 1, v62
	v_lshl_add_u32 v155, v35, 1, v62
	v_cvt_f32_i32_e32 v154, v154
	v_cvt_f32_i32_e32 v155, v155
	v_mul_f32_e32 v154, v130, v154
	v_mul_f32_e32 v155, v146, v155
	v_mul_f32_e32 v154, v70, v154
	v_mul_f32_e32 v155, v70, v155
	v_mul_f32_e64 v156, |v154|, s82
	v_mul_f32_e64 v157, |v155|, s82
	v_fma_f32 v158, v156, s83, 1.0
	v_fma_f32 v159, v157, s83, 1.0
	v_rcp_f32_e32 v158, v158
	v_rcp_f32_e32 v159, v159
	v_mul_f32_e64 v156, v156, -v156
	v_mul_f32_e64 v157, v157, -v157
	v_mul_f32_e32 v156, 0x3fb8aa3b, v156
	v_mul_f32_e32 v157, 0x3fb8aa3b, v157
	v_fmamk_f32 v160, v158, 0x3f87dc22, v110
	v_fmamk_f32 v161, v159, 0x3f87dc22, v110
	v_exp_f32_e32 v156, v156
	v_exp_f32_e32 v157, v157
	v_fmaak_f32 v160, v158, v160, 0x3fb5f0e3
	v_fmaak_f32 v161, v159, v161, 0x3fb5f0e3
	v_fmaak_f32 v160, v158, v160, 0xbe91a98e
	v_fmaak_f32 v161, v159, v161, 0xbe91a98e
	v_fmaak_f32 v160, v158, v160, 0x3e827906
	v_fmaak_f32 v161, v159, v161, 0x3e827906
	v_mul_f32_e32 v158, v158, v160
	v_mul_f32_e32 v159, v159, v161
	v_fma_f32 v156, -v156, v158, 1.0
	v_fma_f32 v157, -v157, v159, 1.0
	v_mul_f32_e32 v162, 0.5, v154
	v_mul_f32_e32 v163, 0.5, v155
	v_bfi_b32 v154, s84, v156, v154
	v_bfi_b32 v155, s84, v157, v155
	v_add_f32_e32 v154, 1.0, v154
	v_add_f32_e32 v155, 1.0, v155
	v_mul_f32_e32 v154, v162, v154
	v_mul_f32_e32 v155, v163, v155
	v_mul_f32_e32 v154, v50, v154
	v_mul_f32_e32 v155, v51, v155
	v_mul_f32_e32 v154, v131, v154
	v_mul_f32_e32 v155, v147, v155
	v_max_f32_e64 v164, |v154|, |v155|
	s_nop 1
	v_max_f32_dpp v164, v164, v164 quad_perm:[1,0,3,2] row_mask:0xf bank_mask:0xf
	s_nop 1
	v_max_f32_dpp v164, v164, v164 quad_perm:[2,3,0,1] row_mask:0xf bank_mask:0xf
	s_nop 1
	v_max_f32_dpp v164, v164, v164 row_half_mirror row_mask:0xf bank_mask:0xf
	s_nop 1
	v_max_f32_dpp v164, v164, v164 row_mirror row_mask:0xf bank_mask:0xf
	s_nop 1
	v_readlane_b32 s46, v164, 32
	v_readlane_b32 s47, v164, 48
; #define LAS __attribute__((address_space(3)))
; __global__ void __launch_bounds__(NTHR, 2) k_main(Args a) {
;     ...
;                 const unsigned ew = *(const LAS unsigned*)(EL + tl * 128 + 2 * lane); const int e0 = (int)(ew & 0xffffu), e1 = (int)(ew >> 16);
;                 typedef int i2v __attribute__((ext_vector_type(2))); const i2v si = *(const LAS i2v*)(ACC + tl * 128 + 2 * lane);
;                 typedef float f2v __attribute__((ext_vector_type(2))); const f2v gt = *(const LAS f2v*)(GL + tl * 128 + 2 * lane); const float xs = XS[t];
;                 const int sx = ((const int*)(XS + T))[t];
;                 const float z0 = (float)(2 * si.x + sx) * SU[e0] * xs, z1 = (float)(2 * si.y + sx) * SU[e1] * xs;
;                 const float a0 = gt.x * gelu_as(z0) * SV[e0], a1 = gt.y * gelu_as(z1) * SV[e1];
;                 const float mx = wave_max_dpp(fmaxf(fabsf(a0), fabsf(a1)));
;                 const float sc = mx > 0.f ? mx * (1.f / 119.f) : 1.f, inv = 1.f / sc;
;                 const int q0 = (int)rintf(a0 * inv), q1 = (int)rintf(a1 * inv);
;                 *(LAS unsigned short*)(AL + tl * 128 + 2 * lane) = (unsigned short)((q0 & 255) | ((q1 & 255) << 8));
;                 const int qs = wave_sum_dpp_i(q0 + q1);
;                 if (lane == 0) { ASC[tl] = sc; SAL[tl] = qs; }
	v_readlane_b32 s12, v164, 0
	v_readlane_b32 s13, v164, 16
	s_nop 1
	v_mov_b32_e32 v164, s47
	v_max_f32_e32 v164, s46, v164
	v_mov_b32_e32 v165, s13
	v_max3_f32 v164, s12, v165, v164
	v_mul_f32_e32 v165, 0x3c09ae41, v164
	v_cmp_lt_f32_e32 vcc, 0, v164
	s_nop 1
	v_cndmask_b32_e32 v164, 1.0, v165, vcc
	v_div_scale_f32 v166, s[12:13], v164, v164, 1.0
	v_rcp_f32_e32 v167, v166
	v_div_scale_f32 v168, vcc, 1.0, v164, 1.0
	v_fma_f32 v169, -v166, v167, 1.0
	v_fmac_f32_e32 v167, v169, v167
	v_mul_f32_e32 v169, v168, v167
	v_fma_f32 v170, -v166, v169, v168
	v_fmac_f32_e32 v169, v170, v167
	v_fma_f32 v166, -v166, v169, v168
	v_div_fmas_f32 v166, v166, v167, v169
	v_div_fixup_f32 v166, v166, v164, 1.0
	v_mul_f32_e32 v154, v166, v154
	v_mul_f32_e32 v155, v166, v155
	v_rndne_f32_e32 v154, v154
	v_rndne_f32_e32 v155, v155
	v_cvt_i32_f32_e32 v154, v154
	v_cvt_i32_f32_e32 v155, v155
	v_perm_b32 v167, v155, v154, s85
	v_add_u32_e32 v154, v154, v155
	ds_write_b16 v90, v167 offset:4096
	s_nop 1
	v_add_u32_dpp v154, v154, v154 quad_perm:[1,0,3,2] row_mask:0xf bank_mask:0xf bound_ctrl:1
	s_nop 1
	v_add_u32_dpp v154, v154, v154 quad_perm:[2,3,0,1] row_mask:0xf bank_mask:0xf bound_ctrl:1
	s_nop 1
	v_add_u32_dpp v154, v154, v154 row_half_mirror row_mask:0xf bank_mask:0xf bound_ctrl:1
	s_nop 1
	v_add_u32_dpp v154, v154, v154 row_mirror row_mask:0xf bank_mask:0xf bound_ctrl:1
	s_nop 1
	v_readlane_b32 s46, v154, 0
	v_readlane_b32 s47, v154, 16
	v_readlane_b32 s12, v154, 32
	v_readlane_b32 s13, v154, 48
	s_nop 1
	s_add_i32 s46, s47, s46
	s_add_i32 s46, s46, s12
	s_add_i32 s46, s46, s13
	s_add_i32 s47, s67, 128
	s_and_saveexec_b64 s[12:13], s[8:9]
	v_mov_b32_e32 v154, s47
	v_mov_b32_e32 v155, s46
	ds_write2st64_b32 v154, v164, v155 offset1:1
	s_or_b64 exec, exec, s[12:13]
	s_waitcnt vmcnt(4)
	v_lshl_add_u32 v154, v36, 1, v63
	v_lshl_add_u32 v155, v37, 1, v63
	v_cvt_f32_i32_e32 v154, v154
	v_cvt_f32_i32_e32 v155, v155
	v_mul_f32_e32 v154, v132, v154
	v_mul_f32_e32 v155, v148, v155
	v_mul_f32_e32 v154, v71, v154
	v_mul_f32_e32 v155, v71, v155
	v_mul_f32_e64 v156, |v154|, s82
	v_mul_f32_e64 v157, |v155|, s82
	v_fma_f32 v158, v156, s83, 1.0
	v_fma_f32 v159, v157, s83, 1.0
	v_rcp_f32_e32 v158, v158
	v_rcp_f32_e32 v159, v159
	v_mul_f32_e64 v156, v156, -v156
	v_mul_f32_e64 v157, v157, -v157
	v_mul_f32_e32 v156, 0x3fb8aa3b, v156
	v_mul_f32_e32 v157, 0x3fb8aa3b, v157
	v_fmamk_f32 v160, v158, 0x3f87dc22, v110
	v_fmamk_f32 v161, v159, 0x3f87dc22, v110
	v_exp_f32_e32 v156, v156
	v_exp_f32_e32 v157, v157
	v_fmaak_f32 v160, v158, v160, 0x3fb5f0e3
	v_fmaak_f32 v161, v159, v161, 0x3fb5f0e3
	v_fmaak_f32 v160, v158, v160, 0xbe91a98e
	v_fmaak_f32 v161, v159, v161, 0xbe91a98e
	v_fmaak_f32 v160, v158, v160, 0x3e827906
	v_fmaak_f32 v161, v159, v161, 0x3e827906
	v_mul_f32_e32 v158, v158, v160
	v_mul_f32_e32 v159, v159, v161
	v_fma_f32 v156, -v156, v158, 1.0
	v_fma_f32 v157, -v157, v159, 1.0
	v_mul_f32_e32 v162, 0.5, v154
	v_mul_f32_e32 v163, 0.5, v155
	v_bfi_b32 v154, s84, v156, v154
	v_bfi_b32 v155, s84, v157, v155
	v_add_f32_e32 v154, 1.0, v154
	v_add_f32_e32 v155, 1.0, v155
	v_mul_f32_e32 v154, v162, v154
	v_mul_f32_e32 v155, v163, v155
	v_mul_f32_e32 v154, v52, v154
	v_mul_f32_e32 v155, v53, v155
	v_mul_f32_e32 v154, v133, v154
	v_mul_f32_e32 v155, v149, v155
	v_max_f32_e64 v164, |v154|, |v155|
	s_nop 1
	v_max_f32_dpp v164, v164, v164 quad_perm:[1,0,3,2] row_mask:0xf bank_mask:0xf
	s_nop 1
	v_max_f32_dpp v164, v164, v164 quad_perm:[2,3,0,1] row_mask:0xf bank_mask:0xf
	s_nop 1
	v_max_f32_dpp v164, v164, v164 row_half_mirror row_mask:0xf bank_mask:0xf
	s_nop 1
	v_max_f32_dpp v164, v164, v164 row_mirror row_mask:0xf bank_mask:0xf
	s_nop 1
	v_readlane_b32 s46, v164, 32
	v_readlane_b32 s47, v164, 48
	v_readlane_b32 s12, v164, 0
	v_readlane_b32 s13, v164, 16
	s_nop 1
	v_mov_b32_e32 v164, s47
	v_max_f32_e32 v164, s46, v164
	v_mov_b32_e32 v165, s13
	v_max3_f32 v164, s12, v165, v164
	v_mul_f32_e32 v165, 0x3c09ae41, v164
	v_cmp_lt_f32_e32 vcc, 0, v164
	s_nop 1
	v_cndmask_b32_e32 v164, 1.0, v165, vcc
	v_div_scale_f32 v166, s[12:13], v164, v164, 1.0
	v_rcp_f32_e32 v167, v166
	v_div_scale_f32 v168, vcc, 1.0, v164, 1.0
	v_fma_f32 v169, -v166, v167, 1.0
	v_fmac_f32_e32 v167, v169, v167
	v_mul_f32_e32 v169, v168, v167
	v_fma_f32 v170, -v166, v169, v168
	v_fmac_f32_e32 v169, v170, v167
	v_fma_f32 v166, -v166, v169, v168
	v_div_fmas_f32 v166, v166, v167, v169
	v_div_fixup_f32 v166, v166, v164, 1.0
	v_mul_f32_e32 v154, v166, v154
	v_mul_f32_e32 v155, v166, v155
	v_rndne_f32_e32 v154, v154
	v_rndne_f32_e32 v155, v155
	v_cvt_i32_f32_e32 v154, v154
	v_cvt_i32_f32_e32 v155, v155
	v_perm_b32 v167, v155, v154, s85
	v_add_u32_e32 v154, v154, v155
	ds_write_b16 v90, v167 offset:5120
	s_nop 1
	v_add_u32_dpp v154, v154, v154 quad_perm:[1,0,3,2] row_mask:0xf bank_mask:0xf bound_ctrl:1
	s_nop 1
	v_add_u32_dpp v154, v154, v154 quad_perm:[2,3,0,1] row_mask:0xf bank_mask:0xf bound_ctrl:1
	s_nop 1
	v_add_u32_dpp v154, v154, v154 row_half_mirror row_mask:0xf bank_mask:0xf bound_ctrl:1
	s_nop 1
	v_add_u32_dpp v154, v154, v154 row_mirror row_mask:0xf bank_mask:0xf bound_ctrl:1
	s_nop 1
	v_readlane_b32 s46, v154, 0
	v_readlane_b32 s47, v154, 16
	v_readlane_b32 s12, v154, 32
	v_readlane_b32 s13, v154, 48
	s_nop 1
	s_add_i32 s46, s47, s46
	s_add_i32 s46, s46, s12
	s_add_i32 s46, s46, s13
	s_add_i32 s47, s67, 160
	s_and_saveexec_b64 s[12:13], s[8:9]
	v_mov_b32_e32 v154, s47
	v_mov_b32_e32 v155, s46
	ds_write2st64_b32 v154, v164, v155 offset1:1
	s_or_b64 exec, exec, s[12:13]
	s_waitcnt vmcnt(2)
; #define LAS __attribute__((address_space(3)))
; __global__ void __launch_bounds__(NTHR, 2) k_main(Args a) {
;     ...
;                 const unsigned ew = *(const LAS unsigned*)(EL + tl * 128 + 2 * lane); const int e0 = (int)(ew & 0xffffu), e1 = (int)(ew >> 16);
;                 typedef int i2v __attribute__((ext_vector_type(2))); const i2v si = *(const LAS i2v*)(ACC + tl * 128 + 2 * lane);
;                 typedef float f2v __attribute__((ext_vector_type(2))); const f2v gt = *(const LAS f2v*)(GL + tl * 128 + 2 * lane); const float xs = XS[t];
;                 const int sx = ((const int*)(XS + T))[t];
;                 const float z0 = (float)(2 * si.x + sx) * SU[e0] * xs, z1 = (float)(2 * si.y + sx) * SU[e1] * xs;
;                 const float a0 = gt.x * gelu_as(z0) * SV[e0], a1 = gt.y * gelu_as(z1) * SV[e1];
;                 const float mx = wave_max_dpp(fmaxf(fabsf(a0), fabsf(a1)));
;                 const float sc = mx > 0.f ? mx * (1.f / 119.f) : 1.f, inv = 1.f / sc;
;                 const int q0 = (int)rintf(a0 * inv), q1 = (int)rintf(a1 * inv);
;                 *(LAS unsigned short*)(AL + tl * 128 + 2 * lane) = (unsigned short)((q0 & 255) | ((q1 & 255) << 8));
;                 const int qs = wave_sum_dpp_i(q0 + q1);
;                 if (lane == 0) { ASC[tl] = sc; SAL[tl] = qs; }
	v_lshl_add_u32 v154, v38, 1, v64
	v_lshl_add_u32 v155, v39, 1, v64
	v_cvt_f32_i32_e32 v154, v154
	v_cvt_f32_i32_e32 v155, v155
	v_mul_f32_e32 v154, v134, v154
	v_mul_f32_e32 v155, v150, v155
	v_mul_f32_e32 v154, v72, v154
	v_mul_f32_e32 v155, v72, v155
	v_mul_f32_e64 v156, |v154|, s82
	v_mul_f32_e64 v157, |v155|, s82
	v_fma_f32 v158, v156, s83, 1.0
	v_fma_f32 v159, v157, s83, 1.0
	v_rcp_f32_e32 v158, v158
	v_rcp_f32_e32 v159, v159
	v_mul_f32_e64 v156, v156, -v156
	v_mul_f32_e64 v157, v157, -v157
	v_mul_f32_e32 v156, 0x3fb8aa3b, v156
	v_mul_f32_e32 v157, 0x3fb8aa3b, v157
	v_fmamk_f32 v160, v158, 0x3f87dc22, v110
	v_fmamk_f32 v161, v159, 0x3f87dc22, v110
	v_exp_f32_e32 v156, v156
	v_exp_f32_e32 v157, v157
	v_fmaak_f32 v160, v158, v160, 0x3fb5f0e3
	v_fmaak_f32 v161, v159, v161, 0x3fb5f0e3
	v_fmaak_f32 v160, v158, v160, 0xbe91a98e
	v_fmaak_f32 v161, v159, v161, 0xbe91a98e
	v_fmaak_f32 v160, v158, v160, 0x3e827906
	v_fmaak_f32 v161, v159, v161, 0x3e827906
	v_mul_f32_e32 v158, v158, v160
	v_mul_f32_e32 v159, v159, v161
	v_fma_f32 v156, -v156, v158, 1.0
	v_fma_f32 v157, -v157, v159, 1.0
	v_mul_f32_e32 v162, 0.5, v154
	v_mul_f32_e32 v163, 0.5, v155
	v_bfi_b32 v154, s84, v156, v154
	v_bfi_b32 v155, s84, v157, v155
	v_add_f32_e32 v154, 1.0, v154
	v_add_f32_e32 v155, 1.0, v155
	v_mul_f32_e32 v154, v162, v154
	v_mul_f32_e32 v155, v163, v155
	v_mul_f32_e32 v154, v54, v154
	v_mul_f32_e32 v155, v55, v155
	v_mul_f32_e32 v154, v135, v154
	v_mul_f32_e32 v155, v151, v155
	v_max_f32_e64 v164, |v154|, |v155|
	s_nop 1
	v_max_f32_dpp v164, v164, v164 quad_perm:[1,0,3,2] row_mask:0xf bank_mask:0xf
	s_nop 1
	v_max_f32_dpp v164, v164, v164 quad_perm:[2,3,0,1] row_mask:0xf bank_mask:0xf
	s_nop 1
	v_max_f32_dpp v164, v164, v164 row_half_mirror row_mask:0xf bank_mask:0xf
	s_nop 1
	v_max_f32_dpp v164, v164, v164 row_mirror row_mask:0xf bank_mask:0xf
	s_nop 1
	v_readlane_b32 s46, v164, 32
	v_readlane_b32 s47, v164, 48
	v_readlane_b32 s12, v164, 0
	v_readlane_b32 s13, v164, 16
	s_nop 1
	v_mov_b32_e32 v164, s47
	v_max_f32_e32 v164, s46, v164
	v_mov_b32_e32 v165, s13
	v_max3_f32 v164, s12, v165, v164
	v_mul_f32_e32 v165, 0x3c09ae41, v164
	v_cmp_lt_f32_e32 vcc, 0, v164
	s_nop 1
	v_cndmask_b32_e32 v164, 1.0, v165, vcc
	v_div_scale_f32 v166, s[12:13], v164, v164, 1.0
	v_rcp_f32_e32 v167, v166
	v_div_scale_f32 v168, vcc, 1.0, v164, 1.0
	v_fma_f32 v169, -v166, v167, 1.0
	v_fmac_f32_e32 v167, v169, v167
	v_mul_f32_e32 v169, v168, v167
	v_fma_f32 v170, -v166, v169, v168
	v_fmac_f32_e32 v169, v170, v167
	v_fma_f32 v166, -v166, v169, v168
	v_div_fmas_f32 v166, v166, v167, v169
	v_div_fixup_f32 v166, v166, v164, 1.0
	v_mul_f32_e32 v154, v166, v154
	v_mul_f32_e32 v155, v166, v155
	v_rndne_f32_e32 v154, v154
	v_rndne_f32_e32 v155, v155
	v_cvt_i32_f32_e32 v154, v154
	v_cvt_i32_f32_e32 v155, v155
	v_perm_b32 v167, v155, v154, s85
	v_add_u32_e32 v154, v154, v155
	ds_write_b16 v90, v167 offset:6144
	s_nop 1
	v_add_u32_dpp v154, v154, v154 quad_perm:[1,0,3,2] row_mask:0xf bank_mask:0xf bound_ctrl:1
	s_nop 1
	v_add_u32_dpp v154, v154, v154 quad_perm:[2,3,0,1] row_mask:0xf bank_mask:0xf bound_ctrl:1
	s_nop 1
	v_add_u32_dpp v154, v154, v154 row_half_mirror row_mask:0xf bank_mask:0xf bound_ctrl:1
	s_nop 1
	v_add_u32_dpp v154, v154, v154 row_mirror row_mask:0xf bank_mask:0xf bound_ctrl:1
	s_nop 1
	v_readlane_b32 s46, v154, 0
	v_readlane_b32 s47, v154, 16
	v_readlane_b32 s12, v154, 32
	v_readlane_b32 s13, v154, 48
	s_nop 1
	s_add_i32 s46, s47, s46
	s_add_i32 s46, s46, s12
	s_add_i32 s46, s46, s13
	s_add_i32 s47, s67, 192
	s_and_saveexec_b64 s[12:13], s[8:9]
	v_mov_b32_e32 v154, s47
	v_mov_b32_e32 v155, s46
	ds_write2st64_b32 v154, v164, v155 offset1:1
	s_or_b64 exec, exec, s[12:13]
	s_waitcnt vmcnt(0)
; #define LAS __attribute__((address_space(3)))
; __global__ void __launch_bounds__(NTHR, 2) k_main(Args a) {
;     ...
;                 const unsigned ew = *(const LAS unsigned*)(EL + tl * 128 + 2 * lane); const int e0 = (int)(ew & 0xffffu), e1 = (int)(ew >> 16);
;                 typedef int i2v __attribute__((ext_vector_type(2))); const i2v si = *(const LAS i2v*)(ACC + tl * 128 + 2 * lane);
;                 typedef float f2v __attribute__((ext_vector_type(2))); const f2v gt = *(const LAS f2v*)(GL + tl * 128 + 2 * lane); const float xs = XS[t];
;                 const int sx = ((const int*)(XS + T))[t];
;                 const float z0 = (float)(2 * si.x + sx) * SU[e0] * xs, z1 = (float)(2 * si.y + sx) * SU[e1] * xs;
;                 const float a0 = gt.x * gelu_as(z0) * SV[e0], a1 = gt.y * gelu_as(z1) * SV[e1];
;                 const float mx = wave_max_dpp(fmaxf(fabsf(a0), fabsf(a1)));
;                 const float sc = mx > 0.f ? mx * (1.f / 119.f) : 1.f, inv = 1.f / sc;
;                 const int q0 = (int)rintf(a0 * inv), q1 = (int)rintf(a1 * inv);
;                 *(LAS unsigned short*)(AL + tl * 128 + 2 * lane) = (unsigned short)((q0 & 255) | ((q1 & 255) << 8));
;                 const int qs = wave_sum_dpp_i(q0 + q1);
;                 if (lane == 0) { ASC[tl] = sc; SAL[tl] = qs; }
	v_lshl_add_u32 v154, v40, 1, v65
	v_lshl_add_u32 v155, v41, 1, v65
	v_cvt_f32_i32_e32 v154, v154
	v_cvt_f32_i32_e32 v155, v155
	v_mul_f32_e32 v154, v136, v154
	v_mul_f32_e32 v155, v152, v155
	v_mul_f32_e32 v154, v73, v154
	v_mul_f32_e32 v155, v73, v155
	v_mul_f32_e64 v156, |v154|, s82
	v_mul_f32_e64 v157, |v155|, s82
	v_fma_f32 v158, v156, s83, 1.0
	v_fma_f32 v159, v157, s83, 1.0
	v_rcp_f32_e32 v158, v158
	v_rcp_f32_e32 v159, v159
	v_mul_f32_e64 v156, v156, -v156
	v_mul_f32_e64 v157, v157, -v157
	v_mul_f32_e32 v156, 0x3fb8aa3b, v156
	v_mul_f32_e32 v157, 0x3fb8aa3b, v157
	v_fmamk_f32 v160, v158, 0x3f87dc22, v110
	v_fmamk_f32 v161, v159, 0x3f87dc22, v110
	v_exp_f32_e32 v156, v156
	v_exp_f32_e32 v157, v157
	v_fmaak_f32 v160, v158, v160, 0x3fb5f0e3
	v_fmaak_f32 v161, v159, v161, 0x3fb5f0e3
	v_fmaak_f32 v160, v158, v160, 0xbe91a98e
	v_fmaak_f32 v161, v159, v161, 0xbe91a98e
	v_fmaak_f32 v160, v158, v160, 0x3e827906
	v_fmaak_f32 v161, v159, v161, 0x3e827906
	v_mul_f32_e32 v158, v158, v160
	v_mul_f32_e32 v159, v159, v161
	v_fma_f32 v156, -v156, v158, 1.0
	v_fma_f32 v157, -v157, v159, 1.0
	v_mul_f32_e32 v162, 0.5, v154
	v_mul_f32_e32 v163, 0.5, v155
	v_bfi_b32 v154, s84, v156, v154
	v_bfi_b32 v155, s84, v157, v155
	v_add_f32_e32 v154, 1.0, v154
	v_add_f32_e32 v155, 1.0, v155
	v_mul_f32_e32 v154, v162, v154
	v_mul_f32_e32 v155, v163, v155
	v_mul_f32_e32 v154, v56, v154
	v_mul_f32_e32 v155, v57, v155
	v_mul_f32_e32 v154, v137, v154
	v_mul_f32_e32 v155, v153, v155
	v_max_f32_e64 v164, |v154|, |v155|
	s_nop 1
	v_max_f32_dpp v164, v164, v164 quad_perm:[1,0,3,2] row_mask:0xf bank_mask:0xf
	s_nop 1
	v_max_f32_dpp v164, v164, v164 quad_perm:[2,3,0,1] row_mask:0xf bank_mask:0xf
	s_nop 1
	v_max_f32_dpp v164, v164, v164 row_half_mirror row_mask:0xf bank_mask:0xf
	s_nop 1
	v_max_f32_dpp v164, v164, v164 row_mirror row_mask:0xf bank_mask:0xf
	s_nop 1
	v_readlane_b32 s46, v164, 32
	v_readlane_b32 s47, v164, 48
	v_readlane_b32 s12, v164, 0
	v_readlane_b32 s13, v164, 16
	s_nop 1
	v_mov_b32_e32 v164, s47
	v_max_f32_e32 v164, s46, v164
	v_mov_b32_e32 v165, s13
	v_max3_f32 v164, s12, v165, v164
	v_mul_f32_e32 v165, 0x3c09ae41, v164
	v_cmp_lt_f32_e32 vcc, 0, v164
	s_nop 1
	v_cndmask_b32_e32 v164, 1.0, v165, vcc
	v_div_scale_f32 v166, s[12:13], v164, v164, 1.0
	v_rcp_f32_e32 v167, v166
	v_div_scale_f32 v168, vcc, 1.0, v164, 1.0
	v_fma_f32 v169, -v166, v167, 1.0
	v_fmac_f32_e32 v167, v169, v167
	v_mul_f32_e32 v169, v168, v167
	v_fma_f32 v170, -v166, v169, v168
	v_fmac_f32_e32 v169, v170, v167
	v_fma_f32 v166, -v166, v169, v168
	v_div_fmas_f32 v166, v166, v167, v169
	v_div_fixup_f32 v166, v166, v164, 1.0
	v_mul_f32_e32 v154, v166, v154
	v_mul_f32_e32 v155, v166, v155
	v_rndne_f32_e32 v154, v154
	v_rndne_f32_e32 v155, v155
	v_cvt_i32_f32_e32 v154, v154
	v_cvt_i32_f32_e32 v155, v155
	v_perm_b32 v167, v155, v154, s85
	v_add_u32_e32 v154, v154, v155
	ds_write_b16 v90, v167 offset:7168
	s_nop 1
	v_add_u32_dpp v154, v154, v154 quad_perm:[1,0,3,2] row_mask:0xf bank_mask:0xf bound_ctrl:1
	s_nop 1
	v_add_u32_dpp v154, v154, v154 quad_perm:[2,3,0,1] row_mask:0xf bank_mask:0xf bound_ctrl:1
	s_nop 1
	v_add_u32_dpp v154, v154, v154 row_half_mirror row_mask:0xf bank_mask:0xf bound_ctrl:1
	s_nop 1
	v_add_u32_dpp v154, v154, v154 row_mirror row_mask:0xf bank_mask:0xf bound_ctrl:1
	s_nop 1
	v_readlane_b32 s46, v154, 0
	v_readlane_b32 s47, v154, 16
	v_readlane_b32 s12, v154, 32
	v_readlane_b32 s13, v154, 48
	s_nop 1
	s_add_i32 s46, s47, s46
	s_add_i32 s46, s46, s12
	s_add_i32 s46, s46, s13
	s_add_i32 s47, s67, 224
	s_and_saveexec_b64 s[12:13], s[8:9]
	v_mov_b32_e32 v154, s47
	v_mov_b32_e32 v155, s46
	ds_write2st64_b32 v154, v164, v155 offset1:1
	s_or_b64 exec, exec, s[12:13]
